# speedup vs baseline: 1.0051x; 1.0051x over previous
; __device__ __forceinline__ float row16_sum(float v) { DPP_ADD(v, 0x128); DPP_ADD(v, 0x124); DPP_ADD(v, 0x122); DPP_ADD(v, 0x121); return v; }
; template <int EPI, int N, int K>
; __device__ __forceinline__ void gemm_phase(const bf16_t* __restrict__ A, const bf16_t* __restrict__ Bt, const EpiArgs ea) {
;     ...
; #pragma unroll
;       for (int ai = 0; ai < 2; ++ai)
; #pragma unroll
;         for (int m = 0; m < 4; ++m)
; #pragma unroll
;           for (int j = 0; j < 4; ++j) {
;             const int row = brow + ai * 128 + wr * 64 + m * 16 + fq * 4 + j;
;             const u32x2 x2 = *(const u32x2*)(ea.outb + (size_t)row * DM + c0);
;             float4 xn;
;             xn.x = __builtin_bit_cast(float, x2[0] << 16) + acc[ai][0][m][0][j]; xn.y = __builtin_bit_cast(float, x2[0] & 0xffff0000u) + acc[ai][0][m][1][j];
;             xn.z = __builtin_bit_cast(float, x2[1] << 16) + acc[ai][1][m][0][j]; xn.w = __builtin_bit_cast(float, x2[1] & 0xffff0000u) + acc[ai][1][m][1][j];
;             u32x2 o = {pk2(xn.x, xn.y), pk2(xn.z, xn.w)};
;             st_wt(ea.outb + (size_t)row * DM + c0, o);
;             float ss = xn.x * xn.x + xn.y * xn.y + xn.z * xn.z + xn.w * xn.w;
;             ss = row16_sum(ss);
;             if (fr == 0) __hip_atomic_fetch_add(ea.rowsq_out + row, (rsq_t)(ss * RSQ_SCALE), __ATOMIC_RELAXED, __HIP_MEMORY_SCOPE_AGENT);
.LBB0_395:
	v_readlane_b32 s2, v236, 14
	v_readlane_b32 s3, v236, 15
	v_lshrrev_b32_e32 v227, 6, v146
	v_lshlrev_b32_e32 v229, 12, v227
	v_bfe_u32 v227, v146, 2, 2
	v_lshl_add_u32 v229, v227, 7, v229
	v_bfe_u32 v227, v145, 4, 2
	v_lshl_add_u32 v229, v227, 5, v229
	v_lshrrev_b32_e32 v227, 6, v145
	v_lshl_add_u32 v229, v227, 3, v229
	v_add_u32_e32 v229, 0x20410, v229
	s_waitcnt vmcnt(42)
	v_lshlrev_b32_e32 v238, 16, v162
	v_and_b32_e32 v239, 0xffff0000, v162
	v_lshlrev_b32_e32 v240, 16, v163
	v_and_b32_e32 v241, 0xffff0000, v163
	v_lshlrev_b32_e32 v242, 16, v164
	v_and_b32_e32 v243, 0xffff0000, v164
	v_lshlrev_b32_e32 v244, 16, v165
	v_and_b32_e32 v245, 0xffff0000, v165
	v_lshlrev_b32_e32 v246, 16, v166
	v_and_b32_e32 v247, 0xffff0000, v166
	v_lshlrev_b32_e32 v248, 16, v167
	v_and_b32_e32 v249, 0xffff0000, v167
	v_lshlrev_b32_e32 v250, 16, v168
	v_and_b32_e32 v251, 0xffff0000, v168
	v_lshlrev_b32_e32 v252, 16, v169
	v_and_b32_e32 v253, 0xffff0000, v169
	v_add_f32_e32 v238, v116, v238
	v_add_f32_e32 v239, v112, v239
	v_add_f32_e32 v240, v124, v240
	v_add_f32_e32 v241, v120, v241
	v_add_f32_e32 v242, v117, v242
	v_add_f32_e32 v243, v113, v243
	v_add_f32_e32 v244, v125, v244
	v_add_f32_e32 v245, v121, v245
	v_add_f32_e32 v246, v118, v246
	v_add_f32_e32 v247, v114, v247
	v_add_f32_e32 v248, v126, v248
	v_add_f32_e32 v249, v122, v249
	v_add_f32_e32 v250, v119, v250
	v_add_f32_e32 v251, v115, v251
	v_add_f32_e32 v252, v127, v252
	v_add_f32_e32 v253, v123, v253
	v_cvt_pk_bf16_f32 v132, v238, v239
	v_cvt_pk_bf16_f32 v133, v240, v241
	v_cvt_pk_bf16_f32 v134, v242, v243
	v_cvt_pk_bf16_f32 v135, v244, v245
	v_cvt_pk_bf16_f32 v136, v246, v247
	v_cvt_pk_bf16_f32 v137, v248, v249
	v_cvt_pk_bf16_f32 v156, v250, v251
	v_cvt_pk_bf16_f32 v157, v252, v253
	global_store_dwordx2 v226, v[132:133], s[2:3] sc1
	v_add_u32_e32 v227, 0x1000, v226
	global_store_dwordx2 v227, v[134:135], s[2:3] sc1
	v_add_u32_e32 v228, 0x2000, v226
	global_store_dwordx2 v228, v[136:137], s[2:3] sc1
	v_add_u32_e32 v227, 0x3000, v226
	global_store_dwordx2 v227, v[156:157], s[2:3] sc1
	v_pk_mul_f32 v[238:239], v[238:239], v[238:239]
	v_pk_mul_f32 v[240:241], v[240:241], v[240:241]
	v_pk_mul_f32 v[242:243], v[242:243], v[242:243]
	v_pk_mul_f32 v[244:245], v[244:245], v[244:245]
	v_pk_mul_f32 v[246:247], v[246:247], v[246:247]
	v_pk_mul_f32 v[248:249], v[248:249], v[248:249]
	v_pk_mul_f32 v[250:251], v[250:251], v[250:251]
	v_pk_mul_f32 v[252:253], v[252:253], v[252:253]
	v_add_f32_e32 v158, v238, v239
	v_add_f32_e32 v159, v242, v243
	v_add_f32_e32 v160, v246, v247
	v_add_f32_e32 v161, v250, v251
	v_add_f32_e32 v158, v240, v158
	v_add_f32_e32 v159, v244, v159
	v_add_f32_e32 v160, v248, v160
	v_add_f32_e32 v161, v252, v161
	v_add_f32_e32 v158, v241, v158
	v_add_f32_e32 v159, v245, v159
	v_add_f32_e32 v160, v249, v160
	v_add_f32_e32 v161, v253, v161
	v_add_f32_dpp v158, v158, v158 row_ror:8 row_mask:0xf bank_mask:0xf bound_ctrl:1
	v_add_f32_dpp v159, v159, v159 row_ror:8 row_mask:0xf bank_mask:0xf bound_ctrl:1
	v_add_f32_dpp v160, v160, v160 row_ror:8 row_mask:0xf bank_mask:0xf bound_ctrl:1
	v_add_f32_dpp v161, v161, v161 row_ror:8 row_mask:0xf bank_mask:0xf bound_ctrl:1
	v_add_f32_dpp v158, v158, v158 row_ror:4 row_mask:0xf bank_mask:0xf bound_ctrl:1
	v_add_f32_dpp v159, v159, v159 row_ror:4 row_mask:0xf bank_mask:0xf bound_ctrl:1
	v_add_f32_dpp v160, v160, v160 row_ror:4 row_mask:0xf bank_mask:0xf bound_ctrl:1
	v_add_f32_dpp v161, v161, v161 row_ror:4 row_mask:0xf bank_mask:0xf bound_ctrl:1
	v_add_f32_dpp v158, v158, v158 row_ror:2 row_mask:0xf bank_mask:0xf bound_ctrl:1
	v_add_f32_dpp v159, v159, v159 row_ror:2 row_mask:0xf bank_mask:0xf bound_ctrl:1
	v_add_f32_dpp v160, v160, v160 row_ror:2 row_mask:0xf bank_mask:0xf bound_ctrl:1
	v_add_f32_dpp v161, v161, v161 row_ror:2 row_mask:0xf bank_mask:0xf bound_ctrl:1
	v_add_f32_dpp v158, v158, v158 row_ror:1 row_mask:0xf bank_mask:0xf bound_ctrl:1
	v_add_f32_dpp v159, v159, v159 row_ror:1 row_mask:0xf bank_mask:0xf bound_ctrl:1
	v_add_f32_dpp v160, v160, v160 row_ror:1 row_mask:0xf bank_mask:0xf bound_ctrl:1
	v_add_f32_dpp v161, v161, v161 row_ror:1 row_mask:0xf bank_mask:0xf bound_ctrl:1
	v_mov_b32_e32 v254, v158
	v_mov_b32_dpp v254, v159 quad_perm:[0,1,2,3] row_mask:0xf bank_mask:0x2
	v_mov_b32_dpp v254, v160 quad_perm:[0,1,2,3] row_mask:0xf bank_mask:0x4
	v_mov_b32_dpp v254, v161 quad_perm:[0,1,2,3] row_mask:0xf bank_mask:0x8
	v_mul_f32_e32 v254, 0x49800000, v254
	v_trunc_f32_e32 v254, v254
	v_mul_f32_e32 v255, 0x2f800000, v254
	v_floor_f32_e32 v255, v255
	v_fmac_f32_e32 v254, 0xcf800000, v255
	v_cvt_u32_f32_e32 v116, v254
	v_cvt_u32_f32_e32 v117, v255
	s_waitcnt vmcnt(42)
; __device__ __forceinline__ float row16_sum(float v) { DPP_ADD(v, 0x128); DPP_ADD(v, 0x124); DPP_ADD(v, 0x122); DPP_ADD(v, 0x121); return v; }
; template <int EPI, int N, int K>
; __device__ __forceinline__ void gemm_phase(const bf16_t* __restrict__ A, const bf16_t* __restrict__ Bt, const EpiArgs ea) {
;     ...
;             const int row = brow + ai * 128 + wr * 64 + m * 16 + fq * 4 + j;
;             const u32x2 x2 = *(const u32x2*)(ea.outb + (size_t)row * DM + c0);
;             float4 xn;
;             xn.x = __builtin_bit_cast(float, x2[0] << 16) + acc[ai][0][m][0][j]; xn.y = __builtin_bit_cast(float, x2[0] & 0xffff0000u) + acc[ai][0][m][1][j];
;             xn.z = __builtin_bit_cast(float, x2[1] << 16) + acc[ai][1][m][0][j]; xn.w = __builtin_bit_cast(float, x2[1] & 0xffff0000u) + acc[ai][1][m][1][j];
;             u32x2 o = {pk2(xn.x, xn.y), pk2(xn.z, xn.w)};
;             st_wt(ea.outb + (size_t)row * DM + c0, o);
;             float ss = xn.x * xn.x + xn.y * xn.y + xn.z * xn.z + xn.w * xn.w;
;             ss = row16_sum(ss);
;             if (fr == 0) __hip_atomic_fetch_add(ea.rowsq_out + row, (rsq_t)(ss * RSQ_SCALE), __ATOMIC_RELAXED, __HIP_MEMORY_SCOPE_AGENT);
	v_lshlrev_b32_e32 v238, 16, v170
	v_and_b32_e32 v239, 0xffff0000, v170
	v_lshlrev_b32_e32 v240, 16, v171
	v_and_b32_e32 v241, 0xffff0000, v171
	v_lshlrev_b32_e32 v242, 16, v172
	v_and_b32_e32 v243, 0xffff0000, v172
	v_lshlrev_b32_e32 v244, 16, v173
	v_and_b32_e32 v245, 0xffff0000, v173
	v_lshlrev_b32_e32 v246, 16, v174
	v_and_b32_e32 v247, 0xffff0000, v174
	v_lshlrev_b32_e32 v248, 16, v175
	v_and_b32_e32 v249, 0xffff0000, v175
	v_lshlrev_b32_e32 v250, 16, v176
	v_and_b32_e32 v251, 0xffff0000, v176
	v_lshlrev_b32_e32 v252, 16, v177
	v_and_b32_e32 v253, 0xffff0000, v177
	v_add_f32_e32 v238, v100, v238
	v_add_f32_e32 v239, v96, v239
	v_add_f32_e32 v240, v108, v240
	v_add_f32_e32 v241, v104, v241
	v_add_f32_e32 v242, v101, v242
	v_add_f32_e32 v243, v97, v243
	v_add_f32_e32 v244, v109, v244
	v_add_f32_e32 v245, v105, v245
	v_add_f32_e32 v246, v102, v246
	v_add_f32_e32 v247, v98, v247
	v_add_f32_e32 v248, v110, v248
	v_add_f32_e32 v249, v106, v249
	v_add_f32_e32 v250, v103, v250
	v_add_f32_e32 v251, v99, v251
	v_add_f32_e32 v252, v111, v252
	v_add_f32_e32 v253, v107, v253
	v_cvt_pk_bf16_f32 v132, v238, v239
	v_cvt_pk_bf16_f32 v133, v240, v241
	v_cvt_pk_bf16_f32 v134, v242, v243
	v_cvt_pk_bf16_f32 v135, v244, v245
	v_cvt_pk_bf16_f32 v136, v246, v247
	v_cvt_pk_bf16_f32 v137, v248, v249
	v_cvt_pk_bf16_f32 v156, v250, v251
	v_cvt_pk_bf16_f32 v157, v252, v253
	v_add_u32_e32 v228, 0x10000, v226
	global_store_dwordx2 v228, v[132:133], s[2:3] sc1
	v_add_u32_e32 v227, 0x11000, v226
	global_store_dwordx2 v227, v[134:135], s[2:3] sc1
	v_add_u32_e32 v228, 0x12000, v226
	global_store_dwordx2 v228, v[136:137], s[2:3] sc1
	v_add_u32_e32 v227, 0x13000, v226
	global_store_dwordx2 v227, v[156:157], s[2:3] sc1
	v_pk_mul_f32 v[238:239], v[238:239], v[238:239]
	v_pk_mul_f32 v[240:241], v[240:241], v[240:241]
	v_pk_mul_f32 v[242:243], v[242:243], v[242:243]
	v_pk_mul_f32 v[244:245], v[244:245], v[244:245]
	v_pk_mul_f32 v[246:247], v[246:247], v[246:247]
	v_pk_mul_f32 v[248:249], v[248:249], v[248:249]
	v_pk_mul_f32 v[250:251], v[250:251], v[250:251]
	v_pk_mul_f32 v[252:253], v[252:253], v[252:253]
	v_add_f32_e32 v158, v238, v239
	v_add_f32_e32 v159, v242, v243
	v_add_f32_e32 v160, v246, v247
	v_add_f32_e32 v161, v250, v251
	v_add_f32_e32 v158, v240, v158
	v_add_f32_e32 v159, v244, v159
	v_add_f32_e32 v160, v248, v160
	v_add_f32_e32 v161, v252, v161
	v_add_f32_e32 v158, v241, v158
	v_add_f32_e32 v159, v245, v159
	v_add_f32_e32 v160, v249, v160
	v_add_f32_e32 v161, v253, v161
	v_add_f32_dpp v158, v158, v158 row_ror:8 row_mask:0xf bank_mask:0xf bound_ctrl:1
	v_add_f32_dpp v159, v159, v159 row_ror:8 row_mask:0xf bank_mask:0xf bound_ctrl:1
	v_add_f32_dpp v160, v160, v160 row_ror:8 row_mask:0xf bank_mask:0xf bound_ctrl:1
	v_add_f32_dpp v161, v161, v161 row_ror:8 row_mask:0xf bank_mask:0xf bound_ctrl:1
	v_add_f32_dpp v158, v158, v158 row_ror:4 row_mask:0xf bank_mask:0xf bound_ctrl:1
	v_add_f32_dpp v159, v159, v159 row_ror:4 row_mask:0xf bank_mask:0xf bound_ctrl:1
	v_add_f32_dpp v160, v160, v160 row_ror:4 row_mask:0xf bank_mask:0xf bound_ctrl:1
	v_add_f32_dpp v161, v161, v161 row_ror:4 row_mask:0xf bank_mask:0xf bound_ctrl:1
	v_add_f32_dpp v158, v158, v158 row_ror:2 row_mask:0xf bank_mask:0xf bound_ctrl:1
	v_add_f32_dpp v159, v159, v159 row_ror:2 row_mask:0xf bank_mask:0xf bound_ctrl:1
	v_add_f32_dpp v160, v160, v160 row_ror:2 row_mask:0xf bank_mask:0xf bound_ctrl:1
	v_add_f32_dpp v161, v161, v161 row_ror:2 row_mask:0xf bank_mask:0xf bound_ctrl:1
	v_add_f32_dpp v158, v158, v158 row_ror:1 row_mask:0xf bank_mask:0xf bound_ctrl:1
	v_add_f32_dpp v159, v159, v159 row_ror:1 row_mask:0xf bank_mask:0xf bound_ctrl:1
	v_add_f32_dpp v160, v160, v160 row_ror:1 row_mask:0xf bank_mask:0xf bound_ctrl:1
	v_add_f32_dpp v161, v161, v161 row_ror:1 row_mask:0xf bank_mask:0xf bound_ctrl:1
	v_mov_b32_e32 v254, v158
	v_mov_b32_dpp v254, v159 quad_perm:[0,1,2,3] row_mask:0xf bank_mask:0x2
	v_mov_b32_dpp v254, v160 quad_perm:[0,1,2,3] row_mask:0xf bank_mask:0x4
	v_mov_b32_dpp v254, v161 quad_perm:[0,1,2,3] row_mask:0xf bank_mask:0x8
	v_mul_f32_e32 v254, 0x49800000, v254
	v_trunc_f32_e32 v254, v254
	v_mul_f32_e32 v255, 0x2f800000, v254
	v_floor_f32_e32 v255, v255
	v_fmac_f32_e32 v254, 0xcf800000, v255
	v_cvt_u32_f32_e32 v100, v254
	v_cvt_u32_f32_e32 v101, v255
	s_waitcnt vmcnt(42)
; __device__ __forceinline__ float row16_sum(float v) { DPP_ADD(v, 0x128); DPP_ADD(v, 0x124); DPP_ADD(v, 0x122); DPP_ADD(v, 0x121); return v; }
; template <int EPI, int N, int K>
; __device__ __forceinline__ void gemm_phase(const bf16_t* __restrict__ A, const bf16_t* __restrict__ Bt, const EpiArgs ea) {
;     ...
;             const int row = brow + ai * 128 + wr * 64 + m * 16 + fq * 4 + j;
;             const u32x2 x2 = *(const u32x2*)(ea.outb + (size_t)row * DM + c0);
;             float4 xn;
;             xn.x = __builtin_bit_cast(float, x2[0] << 16) + acc[ai][0][m][0][j]; xn.y = __builtin_bit_cast(float, x2[0] & 0xffff0000u) + acc[ai][0][m][1][j];
;             xn.z = __builtin_bit_cast(float, x2[1] << 16) + acc[ai][1][m][0][j]; xn.w = __builtin_bit_cast(float, x2[1] & 0xffff0000u) + acc[ai][1][m][1][j];
;             u32x2 o = {pk2(xn.x, xn.y), pk2(xn.z, xn.w)};
;             st_wt(ea.outb + (size_t)row * DM + c0, o);
;             float ss = xn.x * xn.x + xn.y * xn.y + xn.z * xn.z + xn.w * xn.w;
;             ss = row16_sum(ss);
;             if (fr == 0) __hip_atomic_fetch_add(ea.rowsq_out + row, (rsq_t)(ss * RSQ_SCALE), __ATOMIC_RELAXED, __HIP_MEMORY_SCOPE_AGENT);
	v_lshlrev_b32_e32 v238, 16, v178
	v_and_b32_e32 v239, 0xffff0000, v178
	v_lshlrev_b32_e32 v240, 16, v179
	v_and_b32_e32 v241, 0xffff0000, v179
	v_lshlrev_b32_e32 v242, 16, v180
	v_and_b32_e32 v243, 0xffff0000, v180
	v_lshlrev_b32_e32 v244, 16, v181
	v_and_b32_e32 v245, 0xffff0000, v181
	v_lshlrev_b32_e32 v246, 16, v182
	v_and_b32_e32 v247, 0xffff0000, v182
	v_lshlrev_b32_e32 v248, 16, v183
	v_and_b32_e32 v249, 0xffff0000, v183
	v_lshlrev_b32_e32 v250, 16, v184
	v_and_b32_e32 v251, 0xffff0000, v184
	v_lshlrev_b32_e32 v252, 16, v185
	v_and_b32_e32 v253, 0xffff0000, v185
	v_add_f32_e32 v238, v84, v238
	v_add_f32_e32 v239, v80, v239
	v_add_f32_e32 v240, v92, v240
	v_add_f32_e32 v241, v88, v241
	v_add_f32_e32 v242, v85, v242
	v_add_f32_e32 v243, v81, v243
	v_add_f32_e32 v244, v93, v244
	v_add_f32_e32 v245, v89, v245
	v_add_f32_e32 v246, v86, v246
	v_add_f32_e32 v247, v82, v247
	v_add_f32_e32 v248, v94, v248
	v_add_f32_e32 v249, v90, v249
	v_add_f32_e32 v250, v87, v250
	v_add_f32_e32 v251, v83, v251
	v_add_f32_e32 v252, v95, v252
	v_add_f32_e32 v253, v91, v253
	v_cvt_pk_bf16_f32 v132, v238, v239
	v_cvt_pk_bf16_f32 v133, v240, v241
	v_cvt_pk_bf16_f32 v134, v242, v243
	v_cvt_pk_bf16_f32 v135, v244, v245
	v_cvt_pk_bf16_f32 v136, v246, v247
	v_cvt_pk_bf16_f32 v137, v248, v249
	v_cvt_pk_bf16_f32 v156, v250, v251
	v_cvt_pk_bf16_f32 v157, v252, v253
	v_add_u32_e32 v228, 0x20000, v226
	global_store_dwordx2 v228, v[132:133], s[2:3] sc1
	v_add_u32_e32 v227, 0x21000, v226
	global_store_dwordx2 v227, v[134:135], s[2:3] sc1
	v_add_u32_e32 v228, 0x22000, v226
	global_store_dwordx2 v228, v[136:137], s[2:3] sc1
	v_add_u32_e32 v227, 0x23000, v226
	global_store_dwordx2 v227, v[156:157], s[2:3] sc1
	v_pk_mul_f32 v[238:239], v[238:239], v[238:239]
	v_pk_mul_f32 v[240:241], v[240:241], v[240:241]
	v_pk_mul_f32 v[242:243], v[242:243], v[242:243]
	v_pk_mul_f32 v[244:245], v[244:245], v[244:245]
	v_pk_mul_f32 v[246:247], v[246:247], v[246:247]
	v_pk_mul_f32 v[248:249], v[248:249], v[248:249]
	v_pk_mul_f32 v[250:251], v[250:251], v[250:251]
	v_pk_mul_f32 v[252:253], v[252:253], v[252:253]
	v_add_f32_e32 v158, v238, v239
	v_add_f32_e32 v159, v242, v243
	v_add_f32_e32 v160, v246, v247
	v_add_f32_e32 v161, v250, v251
	v_add_f32_e32 v158, v240, v158
	v_add_f32_e32 v159, v244, v159
	v_add_f32_e32 v160, v248, v160
	v_add_f32_e32 v161, v252, v161
	v_add_f32_e32 v158, v241, v158
	v_add_f32_e32 v159, v245, v159
	v_add_f32_e32 v160, v249, v160
	v_add_f32_e32 v161, v253, v161
	v_add_f32_dpp v158, v158, v158 row_ror:8 row_mask:0xf bank_mask:0xf bound_ctrl:1
	v_add_f32_dpp v159, v159, v159 row_ror:8 row_mask:0xf bank_mask:0xf bound_ctrl:1
	v_add_f32_dpp v160, v160, v160 row_ror:8 row_mask:0xf bank_mask:0xf bound_ctrl:1
	v_add_f32_dpp v161, v161, v161 row_ror:8 row_mask:0xf bank_mask:0xf bound_ctrl:1
	v_add_f32_dpp v158, v158, v158 row_ror:4 row_mask:0xf bank_mask:0xf bound_ctrl:1
	v_add_f32_dpp v159, v159, v159 row_ror:4 row_mask:0xf bank_mask:0xf bound_ctrl:1
	v_add_f32_dpp v160, v160, v160 row_ror:4 row_mask:0xf bank_mask:0xf bound_ctrl:1
	v_add_f32_dpp v161, v161, v161 row_ror:4 row_mask:0xf bank_mask:0xf bound_ctrl:1
	v_add_f32_dpp v158, v158, v158 row_ror:2 row_mask:0xf bank_mask:0xf bound_ctrl:1
	v_add_f32_dpp v159, v159, v159 row_ror:2 row_mask:0xf bank_mask:0xf bound_ctrl:1
	v_add_f32_dpp v160, v160, v160 row_ror:2 row_mask:0xf bank_mask:0xf bound_ctrl:1
	v_add_f32_dpp v161, v161, v161 row_ror:2 row_mask:0xf bank_mask:0xf bound_ctrl:1
	v_add_f32_dpp v158, v158, v158 row_ror:1 row_mask:0xf bank_mask:0xf bound_ctrl:1
	v_add_f32_dpp v159, v159, v159 row_ror:1 row_mask:0xf bank_mask:0xf bound_ctrl:1
	v_add_f32_dpp v160, v160, v160 row_ror:1 row_mask:0xf bank_mask:0xf bound_ctrl:1
	v_add_f32_dpp v161, v161, v161 row_ror:1 row_mask:0xf bank_mask:0xf bound_ctrl:1
	v_mov_b32_e32 v254, v158
	v_mov_b32_dpp v254, v159 quad_perm:[0,1,2,3] row_mask:0xf bank_mask:0x2
	v_mov_b32_dpp v254, v160 quad_perm:[0,1,2,3] row_mask:0xf bank_mask:0x4
	v_mov_b32_dpp v254, v161 quad_perm:[0,1,2,3] row_mask:0xf bank_mask:0x8
	v_mul_f32_e32 v254, 0x49800000, v254
	v_trunc_f32_e32 v254, v254
	v_mul_f32_e32 v255, 0x2f800000, v254
	v_floor_f32_e32 v255, v255
	v_fmac_f32_e32 v254, 0xcf800000, v255
	v_cvt_u32_f32_e32 v84, v254
	v_cvt_u32_f32_e32 v85, v255
	s_waitcnt vmcnt(42)
; __device__ __forceinline__ float row16_sum(float v) { DPP_ADD(v, 0x128); DPP_ADD(v, 0x124); DPP_ADD(v, 0x122); DPP_ADD(v, 0x121); return v; }
; template <int EPI, int N, int K>
; __device__ __forceinline__ void gemm_phase(const bf16_t* __restrict__ A, const bf16_t* __restrict__ Bt, const EpiArgs ea) {
;     ...
;             const int row = brow + ai * 128 + wr * 64 + m * 16 + fq * 4 + j;
;             const u32x2 x2 = *(const u32x2*)(ea.outb + (size_t)row * DM + c0);
;             float4 xn;
;             xn.x = __builtin_bit_cast(float, x2[0] << 16) + acc[ai][0][m][0][j]; xn.y = __builtin_bit_cast(float, x2[0] & 0xffff0000u) + acc[ai][0][m][1][j];
;             xn.z = __builtin_bit_cast(float, x2[1] << 16) + acc[ai][1][m][0][j]; xn.w = __builtin_bit_cast(float, x2[1] & 0xffff0000u) + acc[ai][1][m][1][j];
;             u32x2 o = {pk2(xn.x, xn.y), pk2(xn.z, xn.w)};
;             st_wt(ea.outb + (size_t)row * DM + c0, o);
;             float ss = xn.x * xn.x + xn.y * xn.y + xn.z * xn.z + xn.w * xn.w;
;             ss = row16_sum(ss);
;             if (fr == 0) __hip_atomic_fetch_add(ea.rowsq_out + row, (rsq_t)(ss * RSQ_SCALE), __ATOMIC_RELAXED, __HIP_MEMORY_SCOPE_AGENT);
	v_lshlrev_b32_e32 v238, 16, v186
	v_and_b32_e32 v239, 0xffff0000, v186
	v_lshlrev_b32_e32 v240, 16, v187
	v_and_b32_e32 v241, 0xffff0000, v187
	v_lshlrev_b32_e32 v242, 16, v188
	v_and_b32_e32 v243, 0xffff0000, v188
	v_lshlrev_b32_e32 v244, 16, v189
	v_and_b32_e32 v245, 0xffff0000, v189
	v_lshlrev_b32_e32 v246, 16, v190
	v_and_b32_e32 v247, 0xffff0000, v190
	v_lshlrev_b32_e32 v248, 16, v191
	v_and_b32_e32 v249, 0xffff0000, v191
	v_lshlrev_b32_e32 v250, 16, v192
	v_and_b32_e32 v251, 0xffff0000, v192
	v_lshlrev_b32_e32 v252, 16, v193
	v_and_b32_e32 v253, 0xffff0000, v193
	v_add_f32_e32 v238, v68, v238
	v_add_f32_e32 v239, v64, v239
	v_add_f32_e32 v240, v76, v240
	v_add_f32_e32 v241, v72, v241
	v_add_f32_e32 v242, v69, v242
	v_add_f32_e32 v243, v65, v243
	v_add_f32_e32 v244, v77, v244
	v_add_f32_e32 v245, v73, v245
	v_add_f32_e32 v246, v70, v246
	v_add_f32_e32 v247, v66, v247
	v_add_f32_e32 v248, v78, v248
	v_add_f32_e32 v249, v74, v249
	v_add_f32_e32 v250, v71, v250
	v_add_f32_e32 v251, v67, v251
	v_add_f32_e32 v252, v79, v252
	v_add_f32_e32 v253, v75, v253
	v_cvt_pk_bf16_f32 v132, v238, v239
	v_cvt_pk_bf16_f32 v133, v240, v241
	v_cvt_pk_bf16_f32 v134, v242, v243
	v_cvt_pk_bf16_f32 v135, v244, v245
	v_cvt_pk_bf16_f32 v136, v246, v247
	v_cvt_pk_bf16_f32 v137, v248, v249
	v_cvt_pk_bf16_f32 v156, v250, v251
	v_cvt_pk_bf16_f32 v157, v252, v253
	v_add_u32_e32 v228, 0x30000, v226
	global_store_dwordx2 v228, v[132:133], s[2:3] sc1
	v_add_u32_e32 v227, 0x31000, v226
	global_store_dwordx2 v227, v[134:135], s[2:3] sc1
	v_add_u32_e32 v228, 0x32000, v226
	global_store_dwordx2 v228, v[136:137], s[2:3] sc1
	v_add_u32_e32 v227, 0x33000, v226
	global_store_dwordx2 v227, v[156:157], s[2:3] sc1
	v_pk_mul_f32 v[238:239], v[238:239], v[238:239]
	v_pk_mul_f32 v[240:241], v[240:241], v[240:241]
	v_pk_mul_f32 v[242:243], v[242:243], v[242:243]
	v_pk_mul_f32 v[244:245], v[244:245], v[244:245]
	v_pk_mul_f32 v[246:247], v[246:247], v[246:247]
	v_pk_mul_f32 v[248:249], v[248:249], v[248:249]
	v_pk_mul_f32 v[250:251], v[250:251], v[250:251]
	v_pk_mul_f32 v[252:253], v[252:253], v[252:253]
	v_add_f32_e32 v158, v238, v239
	v_add_f32_e32 v159, v242, v243
	v_add_f32_e32 v160, v246, v247
	v_add_f32_e32 v161, v250, v251
	v_add_f32_e32 v158, v240, v158
	v_add_f32_e32 v159, v244, v159
	v_add_f32_e32 v160, v248, v160
	v_add_f32_e32 v161, v252, v161
	v_add_f32_e32 v158, v241, v158
	v_add_f32_e32 v159, v245, v159
	v_add_f32_e32 v160, v249, v160
	v_add_f32_e32 v161, v253, v161
	v_add_f32_dpp v158, v158, v158 row_ror:8 row_mask:0xf bank_mask:0xf bound_ctrl:1
	v_add_f32_dpp v159, v159, v159 row_ror:8 row_mask:0xf bank_mask:0xf bound_ctrl:1
	v_add_f32_dpp v160, v160, v160 row_ror:8 row_mask:0xf bank_mask:0xf bound_ctrl:1
	v_add_f32_dpp v161, v161, v161 row_ror:8 row_mask:0xf bank_mask:0xf bound_ctrl:1
	v_add_f32_dpp v158, v158, v158 row_ror:4 row_mask:0xf bank_mask:0xf bound_ctrl:1
	v_add_f32_dpp v159, v159, v159 row_ror:4 row_mask:0xf bank_mask:0xf bound_ctrl:1
	v_add_f32_dpp v160, v160, v160 row_ror:4 row_mask:0xf bank_mask:0xf bound_ctrl:1
	v_add_f32_dpp v161, v161, v161 row_ror:4 row_mask:0xf bank_mask:0xf bound_ctrl:1
	v_add_f32_dpp v158, v158, v158 row_ror:2 row_mask:0xf bank_mask:0xf bound_ctrl:1
	v_add_f32_dpp v159, v159, v159 row_ror:2 row_mask:0xf bank_mask:0xf bound_ctrl:1
	v_add_f32_dpp v160, v160, v160 row_ror:2 row_mask:0xf bank_mask:0xf bound_ctrl:1
	v_add_f32_dpp v161, v161, v161 row_ror:2 row_mask:0xf bank_mask:0xf bound_ctrl:1
	v_add_f32_dpp v158, v158, v158 row_ror:1 row_mask:0xf bank_mask:0xf bound_ctrl:1
	v_add_f32_dpp v159, v159, v159 row_ror:1 row_mask:0xf bank_mask:0xf bound_ctrl:1
	v_add_f32_dpp v160, v160, v160 row_ror:1 row_mask:0xf bank_mask:0xf bound_ctrl:1
	v_add_f32_dpp v161, v161, v161 row_ror:1 row_mask:0xf bank_mask:0xf bound_ctrl:1
	v_mov_b32_e32 v254, v158
	v_mov_b32_dpp v254, v159 quad_perm:[0,1,2,3] row_mask:0xf bank_mask:0x2
	v_mov_b32_dpp v254, v160 quad_perm:[0,1,2,3] row_mask:0xf bank_mask:0x4
	v_mov_b32_dpp v254, v161 quad_perm:[0,1,2,3] row_mask:0xf bank_mask:0x8
	v_mul_f32_e32 v254, 0x49800000, v254
	v_trunc_f32_e32 v254, v254
	v_mul_f32_e32 v255, 0x2f800000, v254
	v_floor_f32_e32 v255, v255
	v_fmac_f32_e32 v254, 0xcf800000, v255
	v_cvt_u32_f32_e32 v68, v254
	v_cvt_u32_f32_e32 v69, v255
	s_waitcnt vmcnt(42)
; __device__ __forceinline__ float row16_sum(float v) { DPP_ADD(v, 0x128); DPP_ADD(v, 0x124); DPP_ADD(v, 0x122); DPP_ADD(v, 0x121); return v; }
; template <int EPI, int N, int K>
; __device__ __forceinline__ void gemm_phase(const bf16_t* __restrict__ A, const bf16_t* __restrict__ Bt, const EpiArgs ea) {
;     ...
;             const int row = brow + ai * 128 + wr * 64 + m * 16 + fq * 4 + j;
;             const u32x2 x2 = *(const u32x2*)(ea.outb + (size_t)row * DM + c0);
;             float4 xn;
;             xn.x = __builtin_bit_cast(float, x2[0] << 16) + acc[ai][0][m][0][j]; xn.y = __builtin_bit_cast(float, x2[0] & 0xffff0000u) + acc[ai][0][m][1][j];
;             xn.z = __builtin_bit_cast(float, x2[1] << 16) + acc[ai][1][m][0][j]; xn.w = __builtin_bit_cast(float, x2[1] & 0xffff0000u) + acc[ai][1][m][1][j];
;             u32x2 o = {pk2(xn.x, xn.y), pk2(xn.z, xn.w)};
;             st_wt(ea.outb + (size_t)row * DM + c0, o);
;             float ss = xn.x * xn.x + xn.y * xn.y + xn.z * xn.z + xn.w * xn.w;
;             ss = row16_sum(ss);
;             if (fr == 0) __hip_atomic_fetch_add(ea.rowsq_out + row, (rsq_t)(ss * RSQ_SCALE), __ATOMIC_RELAXED, __HIP_MEMORY_SCOPE_AGENT);
	v_lshlrev_b32_e32 v238, 16, v194
	v_and_b32_e32 v239, 0xffff0000, v194
	v_lshlrev_b32_e32 v240, 16, v195
	v_and_b32_e32 v241, 0xffff0000, v195
	v_lshlrev_b32_e32 v242, 16, v196
	v_and_b32_e32 v243, 0xffff0000, v196
	v_lshlrev_b32_e32 v244, 16, v197
	v_and_b32_e32 v245, 0xffff0000, v197
	v_lshlrev_b32_e32 v246, 16, v198
	v_and_b32_e32 v247, 0xffff0000, v198
	v_lshlrev_b32_e32 v248, 16, v199
	v_and_b32_e32 v249, 0xffff0000, v199
	v_lshlrev_b32_e32 v250, 16, v200
	v_and_b32_e32 v251, 0xffff0000, v200
	v_lshlrev_b32_e32 v252, 16, v201
	v_and_b32_e32 v253, 0xffff0000, v201
	v_add_f32_e32 v238, v52, v238
	v_add_f32_e32 v239, v48, v239
	v_add_f32_e32 v240, v60, v240
	v_add_f32_e32 v241, v56, v241
	v_add_f32_e32 v242, v53, v242
	v_add_f32_e32 v243, v49, v243
	v_add_f32_e32 v244, v61, v244
	v_add_f32_e32 v245, v57, v245
	v_add_f32_e32 v246, v54, v246
	v_add_f32_e32 v247, v50, v247
	v_add_f32_e32 v248, v62, v248
	v_add_f32_e32 v249, v58, v249
	v_add_f32_e32 v250, v55, v250
	v_add_f32_e32 v251, v51, v251
	v_add_f32_e32 v252, v63, v252
	v_add_f32_e32 v253, v59, v253
	v_cvt_pk_bf16_f32 v132, v238, v239
	v_cvt_pk_bf16_f32 v133, v240, v241
	v_cvt_pk_bf16_f32 v134, v242, v243
	v_cvt_pk_bf16_f32 v135, v244, v245
	v_cvt_pk_bf16_f32 v136, v246, v247
	v_cvt_pk_bf16_f32 v137, v248, v249
	v_cvt_pk_bf16_f32 v156, v250, v251
	v_cvt_pk_bf16_f32 v157, v252, v253
	v_add_u32_e32 v228, 0x80000, v226
	global_store_dwordx2 v228, v[132:133], s[2:3] sc1
	v_add_u32_e32 v227, 0x81000, v226
	global_store_dwordx2 v227, v[134:135], s[2:3] sc1
	v_add_u32_e32 v228, 0x82000, v226
	global_store_dwordx2 v228, v[136:137], s[2:3] sc1
	v_add_u32_e32 v227, 0x83000, v226
	global_store_dwordx2 v227, v[156:157], s[2:3] sc1
	v_pk_mul_f32 v[238:239], v[238:239], v[238:239]
	v_pk_mul_f32 v[240:241], v[240:241], v[240:241]
	v_pk_mul_f32 v[242:243], v[242:243], v[242:243]
	v_pk_mul_f32 v[244:245], v[244:245], v[244:245]
	v_pk_mul_f32 v[246:247], v[246:247], v[246:247]
	v_pk_mul_f32 v[248:249], v[248:249], v[248:249]
	v_pk_mul_f32 v[250:251], v[250:251], v[250:251]
	v_pk_mul_f32 v[252:253], v[252:253], v[252:253]
	v_add_f32_e32 v158, v238, v239
	v_add_f32_e32 v159, v242, v243
	v_add_f32_e32 v160, v246, v247
	v_add_f32_e32 v161, v250, v251
	v_add_f32_e32 v158, v240, v158
	v_add_f32_e32 v159, v244, v159
	v_add_f32_e32 v160, v248, v160
	v_add_f32_e32 v161, v252, v161
	v_add_f32_e32 v158, v241, v158
	v_add_f32_e32 v159, v245, v159
	v_add_f32_e32 v160, v249, v160
	v_add_f32_e32 v161, v253, v161
	v_add_f32_dpp v158, v158, v158 row_ror:8 row_mask:0xf bank_mask:0xf bound_ctrl:1
	v_add_f32_dpp v159, v159, v159 row_ror:8 row_mask:0xf bank_mask:0xf bound_ctrl:1
	v_add_f32_dpp v160, v160, v160 row_ror:8 row_mask:0xf bank_mask:0xf bound_ctrl:1
	v_add_f32_dpp v161, v161, v161 row_ror:8 row_mask:0xf bank_mask:0xf bound_ctrl:1
	v_add_f32_dpp v158, v158, v158 row_ror:4 row_mask:0xf bank_mask:0xf bound_ctrl:1
	v_add_f32_dpp v159, v159, v159 row_ror:4 row_mask:0xf bank_mask:0xf bound_ctrl:1
	v_add_f32_dpp v160, v160, v160 row_ror:4 row_mask:0xf bank_mask:0xf bound_ctrl:1
	v_add_f32_dpp v161, v161, v161 row_ror:4 row_mask:0xf bank_mask:0xf bound_ctrl:1
	v_add_f32_dpp v158, v158, v158 row_ror:2 row_mask:0xf bank_mask:0xf bound_ctrl:1
	v_add_f32_dpp v159, v159, v159 row_ror:2 row_mask:0xf bank_mask:0xf bound_ctrl:1
	v_add_f32_dpp v160, v160, v160 row_ror:2 row_mask:0xf bank_mask:0xf bound_ctrl:1
	v_add_f32_dpp v161, v161, v161 row_ror:2 row_mask:0xf bank_mask:0xf bound_ctrl:1
	v_add_f32_dpp v158, v158, v158 row_ror:1 row_mask:0xf bank_mask:0xf bound_ctrl:1
	v_add_f32_dpp v159, v159, v159 row_ror:1 row_mask:0xf bank_mask:0xf bound_ctrl:1
	v_add_f32_dpp v160, v160, v160 row_ror:1 row_mask:0xf bank_mask:0xf bound_ctrl:1
	v_add_f32_dpp v161, v161, v161 row_ror:1 row_mask:0xf bank_mask:0xf bound_ctrl:1
	v_mov_b32_e32 v254, v158
	v_mov_b32_dpp v254, v159 quad_perm:[0,1,2,3] row_mask:0xf bank_mask:0x2
	v_mov_b32_dpp v254, v160 quad_perm:[0,1,2,3] row_mask:0xf bank_mask:0x4
	v_mov_b32_dpp v254, v161 quad_perm:[0,1,2,3] row_mask:0xf bank_mask:0x8
	v_mul_f32_e32 v254, 0x49800000, v254
	v_trunc_f32_e32 v254, v254
	v_mul_f32_e32 v255, 0x2f800000, v254
	v_floor_f32_e32 v255, v255
	v_fmac_f32_e32 v254, 0xcf800000, v255
	v_cvt_u32_f32_e32 v52, v254
	v_cvt_u32_f32_e32 v53, v255
	s_waitcnt vmcnt(42)
; __device__ __forceinline__ float row16_sum(float v) { DPP_ADD(v, 0x128); DPP_ADD(v, 0x124); DPP_ADD(v, 0x122); DPP_ADD(v, 0x121); return v; }
; template <int EPI, int N, int K>
; __device__ __forceinline__ void gemm_phase(const bf16_t* __restrict__ A, const bf16_t* __restrict__ Bt, const EpiArgs ea) {
;     ...
;             const int row = brow + ai * 128 + wr * 64 + m * 16 + fq * 4 + j;
;             const u32x2 x2 = *(const u32x2*)(ea.outb + (size_t)row * DM + c0);
;             float4 xn;
;             xn.x = __builtin_bit_cast(float, x2[0] << 16) + acc[ai][0][m][0][j]; xn.y = __builtin_bit_cast(float, x2[0] & 0xffff0000u) + acc[ai][0][m][1][j];
;             xn.z = __builtin_bit_cast(float, x2[1] << 16) + acc[ai][1][m][0][j]; xn.w = __builtin_bit_cast(float, x2[1] & 0xffff0000u) + acc[ai][1][m][1][j];
;             u32x2 o = {pk2(xn.x, xn.y), pk2(xn.z, xn.w)};
;             st_wt(ea.outb + (size_t)row * DM + c0, o);
;             float ss = xn.x * xn.x + xn.y * xn.y + xn.z * xn.z + xn.w * xn.w;
;             ss = row16_sum(ss);
;             if (fr == 0) __hip_atomic_fetch_add(ea.rowsq_out + row, (rsq_t)(ss * RSQ_SCALE), __ATOMIC_RELAXED, __HIP_MEMORY_SCOPE_AGENT);
	v_lshlrev_b32_e32 v238, 16, v202
	v_and_b32_e32 v239, 0xffff0000, v202
	v_lshlrev_b32_e32 v240, 16, v203
	v_and_b32_e32 v241, 0xffff0000, v203
	v_lshlrev_b32_e32 v242, 16, v204
	v_and_b32_e32 v243, 0xffff0000, v204
	v_lshlrev_b32_e32 v244, 16, v205
	v_and_b32_e32 v245, 0xffff0000, v205
	v_lshlrev_b32_e32 v246, 16, v206
	v_and_b32_e32 v247, 0xffff0000, v206
	v_lshlrev_b32_e32 v248, 16, v207
	v_and_b32_e32 v249, 0xffff0000, v207
	v_lshlrev_b32_e32 v250, 16, v208
	v_and_b32_e32 v251, 0xffff0000, v208
	v_lshlrev_b32_e32 v252, 16, v209
	v_and_b32_e32 v253, 0xffff0000, v209
	v_add_f32_e32 v238, v36, v238
	v_add_f32_e32 v239, v32, v239
	v_add_f32_e32 v240, v44, v240
	v_add_f32_e32 v241, v40, v241
	v_add_f32_e32 v242, v37, v242
	v_add_f32_e32 v243, v33, v243
	v_add_f32_e32 v244, v45, v244
	v_add_f32_e32 v245, v41, v245
	v_add_f32_e32 v246, v38, v246
	v_add_f32_e32 v247, v34, v247
	v_add_f32_e32 v248, v46, v248
	v_add_f32_e32 v249, v42, v249
	v_add_f32_e32 v250, v39, v250
	v_add_f32_e32 v251, v35, v251
	v_add_f32_e32 v252, v47, v252
	v_add_f32_e32 v253, v43, v253
	v_cvt_pk_bf16_f32 v132, v238, v239
	v_cvt_pk_bf16_f32 v133, v240, v241
	v_cvt_pk_bf16_f32 v134, v242, v243
	v_cvt_pk_bf16_f32 v135, v244, v245
	v_cvt_pk_bf16_f32 v136, v246, v247
	v_cvt_pk_bf16_f32 v137, v248, v249
	v_cvt_pk_bf16_f32 v156, v250, v251
	v_cvt_pk_bf16_f32 v157, v252, v253
	v_add_u32_e32 v228, 0x90000, v226
	global_store_dwordx2 v228, v[132:133], s[2:3] sc1
	v_add_u32_e32 v227, 0x91000, v226
	global_store_dwordx2 v227, v[134:135], s[2:3] sc1
	v_add_u32_e32 v228, 0x92000, v226
	global_store_dwordx2 v228, v[136:137], s[2:3] sc1
	v_add_u32_e32 v227, 0x93000, v226
	global_store_dwordx2 v227, v[156:157], s[2:3] sc1
	v_pk_mul_f32 v[238:239], v[238:239], v[238:239]
	v_pk_mul_f32 v[240:241], v[240:241], v[240:241]
	v_pk_mul_f32 v[242:243], v[242:243], v[242:243]
	v_pk_mul_f32 v[244:245], v[244:245], v[244:245]
	v_pk_mul_f32 v[246:247], v[246:247], v[246:247]
	v_pk_mul_f32 v[248:249], v[248:249], v[248:249]
	v_pk_mul_f32 v[250:251], v[250:251], v[250:251]
	v_pk_mul_f32 v[252:253], v[252:253], v[252:253]
	v_add_f32_e32 v158, v238, v239
	v_add_f32_e32 v159, v242, v243
	v_add_f32_e32 v160, v246, v247
	v_add_f32_e32 v161, v250, v251
	v_add_f32_e32 v158, v240, v158
	v_add_f32_e32 v159, v244, v159
	v_add_f32_e32 v160, v248, v160
	v_add_f32_e32 v161, v252, v161
	v_add_f32_e32 v158, v241, v158
	v_add_f32_e32 v159, v245, v159
	v_add_f32_e32 v160, v249, v160
	v_add_f32_e32 v161, v253, v161
	v_add_f32_dpp v158, v158, v158 row_ror:8 row_mask:0xf bank_mask:0xf bound_ctrl:1
	v_add_f32_dpp v159, v159, v159 row_ror:8 row_mask:0xf bank_mask:0xf bound_ctrl:1
	v_add_f32_dpp v160, v160, v160 row_ror:8 row_mask:0xf bank_mask:0xf bound_ctrl:1
	v_add_f32_dpp v161, v161, v161 row_ror:8 row_mask:0xf bank_mask:0xf bound_ctrl:1
	v_add_f32_dpp v158, v158, v158 row_ror:4 row_mask:0xf bank_mask:0xf bound_ctrl:1
	v_add_f32_dpp v159, v159, v159 row_ror:4 row_mask:0xf bank_mask:0xf bound_ctrl:1
	v_add_f32_dpp v160, v160, v160 row_ror:4 row_mask:0xf bank_mask:0xf bound_ctrl:1
	v_add_f32_dpp v161, v161, v161 row_ror:4 row_mask:0xf bank_mask:0xf bound_ctrl:1
	v_add_f32_dpp v158, v158, v158 row_ror:2 row_mask:0xf bank_mask:0xf bound_ctrl:1
	v_add_f32_dpp v159, v159, v159 row_ror:2 row_mask:0xf bank_mask:0xf bound_ctrl:1
	v_add_f32_dpp v160, v160, v160 row_ror:2 row_mask:0xf bank_mask:0xf bound_ctrl:1
	v_add_f32_dpp v161, v161, v161 row_ror:2 row_mask:0xf bank_mask:0xf bound_ctrl:1
	v_add_f32_dpp v158, v158, v158 row_ror:1 row_mask:0xf bank_mask:0xf bound_ctrl:1
	v_add_f32_dpp v159, v159, v159 row_ror:1 row_mask:0xf bank_mask:0xf bound_ctrl:1
	v_add_f32_dpp v160, v160, v160 row_ror:1 row_mask:0xf bank_mask:0xf bound_ctrl:1
	v_add_f32_dpp v161, v161, v161 row_ror:1 row_mask:0xf bank_mask:0xf bound_ctrl:1
	v_mov_b32_e32 v254, v158
	v_mov_b32_dpp v254, v159 quad_perm:[0,1,2,3] row_mask:0xf bank_mask:0x2
	v_mov_b32_dpp v254, v160 quad_perm:[0,1,2,3] row_mask:0xf bank_mask:0x4
	v_mov_b32_dpp v254, v161 quad_perm:[0,1,2,3] row_mask:0xf bank_mask:0x8
	v_mul_f32_e32 v254, 0x49800000, v254
	v_trunc_f32_e32 v254, v254
	v_mul_f32_e32 v255, 0x2f800000, v254
	v_floor_f32_e32 v255, v255
	v_fmac_f32_e32 v254, 0xcf800000, v255
	v_cvt_u32_f32_e32 v36, v254
	v_cvt_u32_f32_e32 v37, v255
	s_waitcnt vmcnt(42)
; __device__ __forceinline__ float row16_sum(float v) { DPP_ADD(v, 0x128); DPP_ADD(v, 0x124); DPP_ADD(v, 0x122); DPP_ADD(v, 0x121); return v; }
; template <int EPI, int N, int K>
; __device__ __forceinline__ void gemm_phase(const bf16_t* __restrict__ A, const bf16_t* __restrict__ Bt, const EpiArgs ea) {
;     ...
;             const int row = brow + ai * 128 + wr * 64 + m * 16 + fq * 4 + j;
;             const u32x2 x2 = *(const u32x2*)(ea.outb + (size_t)row * DM + c0);
;             float4 xn;
;             xn.x = __builtin_bit_cast(float, x2[0] << 16) + acc[ai][0][m][0][j]; xn.y = __builtin_bit_cast(float, x2[0] & 0xffff0000u) + acc[ai][0][m][1][j];
;             xn.z = __builtin_bit_cast(float, x2[1] << 16) + acc[ai][1][m][0][j]; xn.w = __builtin_bit_cast(float, x2[1] & 0xffff0000u) + acc[ai][1][m][1][j];
;             u32x2 o = {pk2(xn.x, xn.y), pk2(xn.z, xn.w)};
;             st_wt(ea.outb + (size_t)row * DM + c0, o);
;             float ss = xn.x * xn.x + xn.y * xn.y + xn.z * xn.z + xn.w * xn.w;
;             ss = row16_sum(ss);
;             if (fr == 0) __hip_atomic_fetch_add(ea.rowsq_out + row, (rsq_t)(ss * RSQ_SCALE), __ATOMIC_RELAXED, __HIP_MEMORY_SCOPE_AGENT);
	v_lshlrev_b32_e32 v238, 16, v210
	v_and_b32_e32 v239, 0xffff0000, v210
	v_lshlrev_b32_e32 v240, 16, v211
	v_and_b32_e32 v241, 0xffff0000, v211
	v_lshlrev_b32_e32 v242, 16, v212
	v_and_b32_e32 v243, 0xffff0000, v212
	v_lshlrev_b32_e32 v244, 16, v213
	v_and_b32_e32 v245, 0xffff0000, v213
	v_lshlrev_b32_e32 v246, 16, v214
	v_and_b32_e32 v247, 0xffff0000, v214
	v_lshlrev_b32_e32 v248, 16, v215
	v_and_b32_e32 v249, 0xffff0000, v215
	v_lshlrev_b32_e32 v250, 16, v216
	v_and_b32_e32 v251, 0xffff0000, v216
	v_lshlrev_b32_e32 v252, 16, v217
	v_and_b32_e32 v253, 0xffff0000, v217
	v_add_f32_e32 v238, v20, v238
	v_add_f32_e32 v239, v16, v239
	v_add_f32_e32 v240, v28, v240
	v_add_f32_e32 v241, v24, v241
	v_add_f32_e32 v242, v21, v242
	v_add_f32_e32 v243, v17, v243
	v_add_f32_e32 v244, v29, v244
	v_add_f32_e32 v245, v25, v245
	v_add_f32_e32 v246, v22, v246
	v_add_f32_e32 v247, v18, v247
	v_add_f32_e32 v248, v30, v248
	v_add_f32_e32 v249, v26, v249
	v_add_f32_e32 v250, v23, v250
	v_add_f32_e32 v251, v19, v251
	v_add_f32_e32 v252, v31, v252
	v_add_f32_e32 v253, v27, v253
	v_cvt_pk_bf16_f32 v132, v238, v239
	v_cvt_pk_bf16_f32 v133, v240, v241
	v_cvt_pk_bf16_f32 v134, v242, v243
	v_cvt_pk_bf16_f32 v135, v244, v245
	v_cvt_pk_bf16_f32 v136, v246, v247
	v_cvt_pk_bf16_f32 v137, v248, v249
	v_cvt_pk_bf16_f32 v156, v250, v251
	v_cvt_pk_bf16_f32 v157, v252, v253
	v_add_u32_e32 v228, 0xa0000, v226
	global_store_dwordx2 v228, v[132:133], s[2:3] sc1
	v_add_u32_e32 v227, 0xa1000, v226
	global_store_dwordx2 v227, v[134:135], s[2:3] sc1
	v_add_u32_e32 v228, 0xa2000, v226
	global_store_dwordx2 v228, v[136:137], s[2:3] sc1
	v_add_u32_e32 v227, 0xa3000, v226
	global_store_dwordx2 v227, v[156:157], s[2:3] sc1
	v_pk_mul_f32 v[238:239], v[238:239], v[238:239]
	v_pk_mul_f32 v[240:241], v[240:241], v[240:241]
	v_pk_mul_f32 v[242:243], v[242:243], v[242:243]
	v_pk_mul_f32 v[244:245], v[244:245], v[244:245]
	v_pk_mul_f32 v[246:247], v[246:247], v[246:247]
	v_pk_mul_f32 v[248:249], v[248:249], v[248:249]
	v_pk_mul_f32 v[250:251], v[250:251], v[250:251]
	v_pk_mul_f32 v[252:253], v[252:253], v[252:253]
	v_add_f32_e32 v158, v238, v239
	v_add_f32_e32 v159, v242, v243
	v_add_f32_e32 v160, v246, v247
	v_add_f32_e32 v161, v250, v251
	v_add_f32_e32 v158, v240, v158
	v_add_f32_e32 v159, v244, v159
	v_add_f32_e32 v160, v248, v160
	v_add_f32_e32 v161, v252, v161
	v_add_f32_e32 v158, v241, v158
	v_add_f32_e32 v159, v245, v159
	v_add_f32_e32 v160, v249, v160
	v_add_f32_e32 v161, v253, v161
	v_add_f32_dpp v158, v158, v158 row_ror:8 row_mask:0xf bank_mask:0xf bound_ctrl:1
	v_add_f32_dpp v159, v159, v159 row_ror:8 row_mask:0xf bank_mask:0xf bound_ctrl:1
	v_add_f32_dpp v160, v160, v160 row_ror:8 row_mask:0xf bank_mask:0xf bound_ctrl:1
	v_add_f32_dpp v161, v161, v161 row_ror:8 row_mask:0xf bank_mask:0xf bound_ctrl:1
	v_add_f32_dpp v158, v158, v158 row_ror:4 row_mask:0xf bank_mask:0xf bound_ctrl:1
	v_add_f32_dpp v159, v159, v159 row_ror:4 row_mask:0xf bank_mask:0xf bound_ctrl:1
	v_add_f32_dpp v160, v160, v160 row_ror:4 row_mask:0xf bank_mask:0xf bound_ctrl:1
	v_add_f32_dpp v161, v161, v161 row_ror:4 row_mask:0xf bank_mask:0xf bound_ctrl:1
	v_add_f32_dpp v158, v158, v158 row_ror:2 row_mask:0xf bank_mask:0xf bound_ctrl:1
	v_add_f32_dpp v159, v159, v159 row_ror:2 row_mask:0xf bank_mask:0xf bound_ctrl:1
	v_add_f32_dpp v160, v160, v160 row_ror:2 row_mask:0xf bank_mask:0xf bound_ctrl:1
	v_add_f32_dpp v161, v161, v161 row_ror:2 row_mask:0xf bank_mask:0xf bound_ctrl:1
	v_add_f32_dpp v158, v158, v158 row_ror:1 row_mask:0xf bank_mask:0xf bound_ctrl:1
	v_add_f32_dpp v159, v159, v159 row_ror:1 row_mask:0xf bank_mask:0xf bound_ctrl:1
	v_add_f32_dpp v160, v160, v160 row_ror:1 row_mask:0xf bank_mask:0xf bound_ctrl:1
	v_add_f32_dpp v161, v161, v161 row_ror:1 row_mask:0xf bank_mask:0xf bound_ctrl:1
	v_mov_b32_e32 v254, v158
	v_mov_b32_dpp v254, v159 quad_perm:[0,1,2,3] row_mask:0xf bank_mask:0x2
	v_mov_b32_dpp v254, v160 quad_perm:[0,1,2,3] row_mask:0xf bank_mask:0x4
	v_mov_b32_dpp v254, v161 quad_perm:[0,1,2,3] row_mask:0xf bank_mask:0x8
	v_mul_f32_e32 v254, 0x49800000, v254
	v_trunc_f32_e32 v254, v254
	v_mul_f32_e32 v255, 0x2f800000, v254
	v_floor_f32_e32 v255, v255
	v_fmac_f32_e32 v254, 0xcf800000, v255
	v_cvt_u32_f32_e32 v20, v254
	v_cvt_u32_f32_e32 v21, v255
	s_waitcnt vmcnt(42)
; __device__ __forceinline__ float row16_sum(float v) { DPP_ADD(v, 0x128); DPP_ADD(v, 0x124); DPP_ADD(v, 0x122); DPP_ADD(v, 0x121); return v; }
; template <int EPI, int N, int K>
; __device__ __forceinline__ void gemm_phase(const bf16_t* __restrict__ A, const bf16_t* __restrict__ Bt, const EpiArgs ea) {
;     ...
;             const int row = brow + ai * 128 + wr * 64 + m * 16 + fq * 4 + j;
;             const u32x2 x2 = *(const u32x2*)(ea.outb + (size_t)row * DM + c0);
;             float4 xn;
;             xn.x = __builtin_bit_cast(float, x2[0] << 16) + acc[ai][0][m][0][j]; xn.y = __builtin_bit_cast(float, x2[0] & 0xffff0000u) + acc[ai][0][m][1][j];
;             xn.z = __builtin_bit_cast(float, x2[1] << 16) + acc[ai][1][m][0][j]; xn.w = __builtin_bit_cast(float, x2[1] & 0xffff0000u) + acc[ai][1][m][1][j];
;             u32x2 o = {pk2(xn.x, xn.y), pk2(xn.z, xn.w)};
;             st_wt(ea.outb + (size_t)row * DM + c0, o);
;             float ss = xn.x * xn.x + xn.y * xn.y + xn.z * xn.z + xn.w * xn.w;
;             ss = row16_sum(ss);
;             if (fr == 0) __hip_atomic_fetch_add(ea.rowsq_out + row, (rsq_t)(ss * RSQ_SCALE), __ATOMIC_RELAXED, __HIP_MEMORY_SCOPE_AGENT);
	v_lshlrev_b32_e32 v238, 16, v218
	v_and_b32_e32 v239, 0xffff0000, v218
	v_lshlrev_b32_e32 v240, 16, v219
	v_and_b32_e32 v241, 0xffff0000, v219
	v_lshlrev_b32_e32 v242, 16, v220
	v_and_b32_e32 v243, 0xffff0000, v220
	v_lshlrev_b32_e32 v244, 16, v221
	v_and_b32_e32 v245, 0xffff0000, v221
	v_lshlrev_b32_e32 v246, 16, v222
	v_and_b32_e32 v247, 0xffff0000, v222
	v_lshlrev_b32_e32 v248, 16, v223
	v_and_b32_e32 v249, 0xffff0000, v223
	v_lshlrev_b32_e32 v250, 16, v224
	v_and_b32_e32 v251, 0xffff0000, v224
	v_lshlrev_b32_e32 v252, 16, v225
	v_and_b32_e32 v253, 0xffff0000, v225
	v_add_f32_e32 v238, v8, v238
	v_add_f32_e32 v239, v12, v239
	v_add_f32_e32 v240, v4, v240
	v_add_f32_e32 v241, v0, v241
	v_add_f32_e32 v242, v9, v242
	v_add_f32_e32 v243, v13, v243
	v_add_f32_e32 v244, v5, v244
	v_add_f32_e32 v245, v1, v245
	v_add_f32_e32 v246, v10, v246
	v_add_f32_e32 v247, v14, v247
	v_add_f32_e32 v248, v6, v248
	v_add_f32_e32 v249, v2, v249
	v_add_f32_e32 v250, v11, v250
	v_add_f32_e32 v251, v15, v251
	v_add_f32_e32 v252, v7, v252
	v_add_f32_e32 v253, v3, v253
	v_cvt_pk_bf16_f32 v132, v238, v239
	v_cvt_pk_bf16_f32 v133, v240, v241
	v_cvt_pk_bf16_f32 v134, v242, v243
	v_cvt_pk_bf16_f32 v135, v244, v245
	v_cvt_pk_bf16_f32 v136, v246, v247
	v_cvt_pk_bf16_f32 v137, v248, v249
	v_cvt_pk_bf16_f32 v156, v250, v251
	v_cvt_pk_bf16_f32 v157, v252, v253
	v_add_u32_e32 v228, 0xb0000, v226
	global_store_dwordx2 v228, v[132:133], s[2:3] sc1
	v_add_u32_e32 v227, 0xb1000, v226
	global_store_dwordx2 v227, v[134:135], s[2:3] sc1
	v_add_u32_e32 v228, 0xb2000, v226
	global_store_dwordx2 v228, v[136:137], s[2:3] sc1
	v_add_u32_e32 v227, 0xb3000, v226
	global_store_dwordx2 v227, v[156:157], s[2:3] sc1
	v_pk_mul_f32 v[238:239], v[238:239], v[238:239]
	v_pk_mul_f32 v[240:241], v[240:241], v[240:241]
	v_pk_mul_f32 v[242:243], v[242:243], v[242:243]
	v_pk_mul_f32 v[244:245], v[244:245], v[244:245]
	v_pk_mul_f32 v[246:247], v[246:247], v[246:247]
	v_pk_mul_f32 v[248:249], v[248:249], v[248:249]
	v_pk_mul_f32 v[250:251], v[250:251], v[250:251]
	v_pk_mul_f32 v[252:253], v[252:253], v[252:253]
	v_add_f32_e32 v158, v238, v239
	v_add_f32_e32 v159, v242, v243
	v_add_f32_e32 v160, v246, v247
	v_add_f32_e32 v161, v250, v251
	v_add_f32_e32 v158, v240, v158
	v_add_f32_e32 v159, v244, v159
	v_add_f32_e32 v160, v248, v160
	v_add_f32_e32 v161, v252, v161
	v_add_f32_e32 v158, v241, v158
	v_add_f32_e32 v159, v245, v159
	v_add_f32_e32 v160, v249, v160
	v_add_f32_e32 v161, v253, v161
	v_add_f32_dpp v158, v158, v158 row_ror:8 row_mask:0xf bank_mask:0xf bound_ctrl:1
	v_add_f32_dpp v159, v159, v159 row_ror:8 row_mask:0xf bank_mask:0xf bound_ctrl:1
	v_add_f32_dpp v160, v160, v160 row_ror:8 row_mask:0xf bank_mask:0xf bound_ctrl:1
	v_add_f32_dpp v161, v161, v161 row_ror:8 row_mask:0xf bank_mask:0xf bound_ctrl:1
	v_add_f32_dpp v158, v158, v158 row_ror:4 row_mask:0xf bank_mask:0xf bound_ctrl:1
	v_add_f32_dpp v159, v159, v159 row_ror:4 row_mask:0xf bank_mask:0xf bound_ctrl:1
	v_add_f32_dpp v160, v160, v160 row_ror:4 row_mask:0xf bank_mask:0xf bound_ctrl:1
	v_add_f32_dpp v161, v161, v161 row_ror:4 row_mask:0xf bank_mask:0xf bound_ctrl:1
	v_add_f32_dpp v158, v158, v158 row_ror:2 row_mask:0xf bank_mask:0xf bound_ctrl:1
	v_add_f32_dpp v159, v159, v159 row_ror:2 row_mask:0xf bank_mask:0xf bound_ctrl:1
	v_add_f32_dpp v160, v160, v160 row_ror:2 row_mask:0xf bank_mask:0xf bound_ctrl:1
	v_add_f32_dpp v161, v161, v161 row_ror:2 row_mask:0xf bank_mask:0xf bound_ctrl:1
	v_add_f32_dpp v158, v158, v158 row_ror:1 row_mask:0xf bank_mask:0xf bound_ctrl:1
	v_add_f32_dpp v159, v159, v159 row_ror:1 row_mask:0xf bank_mask:0xf bound_ctrl:1
	v_add_f32_dpp v160, v160, v160 row_ror:1 row_mask:0xf bank_mask:0xf bound_ctrl:1
	v_add_f32_dpp v161, v161, v161 row_ror:1 row_mask:0xf bank_mask:0xf bound_ctrl:1
	v_mov_b32_e32 v254, v158
	v_mov_b32_dpp v254, v159 quad_perm:[0,1,2,3] row_mask:0xf bank_mask:0x2
	v_mov_b32_dpp v254, v160 quad_perm:[0,1,2,3] row_mask:0xf bank_mask:0x4
	v_mov_b32_dpp v254, v161 quad_perm:[0,1,2,3] row_mask:0xf bank_mask:0x8
	v_mul_f32_e32 v254, 0x49800000, v254
	v_trunc_f32_e32 v254, v254
	v_mul_f32_e32 v255, 0x2f800000, v254
	v_floor_f32_e32 v255, v255
	v_fmac_f32_e32 v254, 0xcf800000, v255
	v_cvt_u32_f32_e32 v8, v254
	v_cvt_u32_f32_e32 v9, v255
	v_and_b32_e32 v227, 12, v145
	v_cmp_eq_u32_e32 vcc, 0, v227
	s_and_b64 exec, exec, vcc
	ds_write_b64 v229, v[116:117]
	ds_write_b64 v229, v[100:101] offset:512
	ds_write_b64 v229, v[84:85] offset:1024
	ds_write_b64 v229, v[68:69] offset:1536
	ds_write_b64 v229, v[52:53] offset:2048
	ds_write_b64 v229, v[36:37] offset:2560
	ds_write_b64 v229, v[20:21] offset:3072
	ds_write_b64 v229, v[8:9] offset:3584
	s_mov_b64 exec, -1
	v_bfe_u32 v227, v146, 2, 2
	v_bfe_u32 v228, v145, 2, 4
	v_lshl_add_u32 v227, v227, 4, v228
	v_lshrrev_b32_e32 v228, 6, v145
	v_lshl_add_u32 v228, v228, 5, v227
	v_lshrrev_b32_e32 v230, 6, v146
	v_lshlrev_b32_e32 v231, 12, v230
	v_lshl_add_u32 v231, v228, 5, v231
	v_add_u32_e32 v231, 0x20410, v231
	v_cmp_gt_u32_e32 vcc, 32, v227
	v_lshrrev_b32_e32 v227, 6, v228
	v_lshlrev_b32_e32 v227, 7, v227
	v_and_b32_e32 v228, 63, v228
	v_add3_u32 v227, v227, v228, s31
	v_lshl_add_u32 v227, v230, 6, v227
	v_lshlrev_b32_e32 v227, 3, v227
	s_waitcnt lgkmcnt(0)
	s_barrier
	s_and_b64 exec, exec, vcc
	ds_read_b128 v[238:241], v231
	ds_read_b128 v[242:245], v231 offset:16
	s_waitcnt lgkmcnt(0)
	v_add_co_u32_e32 v246, vcc, v238, v240
	s_nop 1
	v_addc_co_u32_e32 v247, vcc, v239, v241, vcc
	v_add_co_u32_e32 v246, vcc, v246, v242
	s_nop 1
	v_addc_co_u32_e32 v247, vcc, v247, v243, vcc
	v_add_co_u32_e32 v246, vcc, v246, v244
	s_nop 1
	v_addc_co_u32_e32 v247, vcc, v247, v245, vcc
	global_atomic_add_x2 v227, v[246:247], s[0:1]
	s_mov_b64 exec, -1
	s_mov_b64 s[2:3], -1
	s_branch .LBB0_384

; __device__ __forceinline__ float row16_sum(float v) { DPP_ADD(v, 0x128); DPP_ADD(v, 0x124); DPP_ADD(v, 0x122); DPP_ADD(v, 0x121); return v; }
; template <int EPI, int N, int K>
; __device__ __forceinline__ void gemm_phase(const bf16_t* __restrict__ A, const bf16_t* __restrict__ Bt, const EpiArgs ea) {
;     ...
; #pragma unroll
;       for (int ai = 0; ai < 2; ++ai)
; #pragma unroll
;         for (int m = 0; m < 4; ++m)
; #pragma unroll
;           for (int j = 0; j < 4; ++j) {
;             const int row = brow + ai * 128 + wr * 64 + m * 16 + fq * 4 + j;
;             const u32x2 x2 = *(const u32x2*)(ea.outb + (size_t)row * DM + c0);
;             float4 xn;
;             xn.x = __builtin_bit_cast(float, x2[0] << 16) + acc[ai][0][m][0][j]; xn.y = __builtin_bit_cast(float, x2[0] & 0xffff0000u) + acc[ai][0][m][1][j];
;             xn.z = __builtin_bit_cast(float, x2[1] << 16) + acc[ai][1][m][0][j]; xn.w = __builtin_bit_cast(float, x2[1] & 0xffff0000u) + acc[ai][1][m][1][j];
;             u32x2 o = {pk2(xn.x, xn.y), pk2(xn.z, xn.w)};
;             st_wt(ea.outb + (size_t)row * DM + c0, o);
;             float ss = xn.x * xn.x + xn.y * xn.y + xn.z * xn.z + xn.w * xn.w;
;             ss = row16_sum(ss);
;             if (fr == 0) __hip_atomic_fetch_add(ea.rowsq_out + row, (rsq_t)(ss * RSQ_SCALE), __ATOMIC_RELAXED, __HIP_MEMORY_SCOPE_AGENT);
.LBB0_573:
	v_readlane_b32 s2, v236, 14
	v_readlane_b32 s3, v236, 15
	v_lshrrev_b32_e32 v227, 6, v146
	v_lshlrev_b32_e32 v229, 12, v227
	v_bfe_u32 v227, v146, 2, 2
	v_lshl_add_u32 v229, v227, 7, v229
	v_bfe_u32 v227, v145, 4, 2
	v_lshl_add_u32 v229, v227, 5, v229
	v_lshrrev_b32_e32 v227, 6, v145
	v_lshl_add_u32 v229, v227, 3, v229
	v_add_u32_e32 v229, 0x20410, v229
	s_waitcnt vmcnt(42)
	v_lshlrev_b32_e32 v238, 16, v162
	v_and_b32_e32 v239, 0xffff0000, v162
	v_lshlrev_b32_e32 v240, 16, v163
	v_and_b32_e32 v241, 0xffff0000, v163
	v_lshlrev_b32_e32 v242, 16, v164
	v_and_b32_e32 v243, 0xffff0000, v164
	v_lshlrev_b32_e32 v244, 16, v165
	v_and_b32_e32 v245, 0xffff0000, v165
	v_lshlrev_b32_e32 v246, 16, v166
	v_and_b32_e32 v247, 0xffff0000, v166
	v_lshlrev_b32_e32 v248, 16, v167
	v_and_b32_e32 v249, 0xffff0000, v167
	v_lshlrev_b32_e32 v250, 16, v168
	v_and_b32_e32 v251, 0xffff0000, v168
	v_lshlrev_b32_e32 v252, 16, v169
	v_and_b32_e32 v253, 0xffff0000, v169
	v_add_f32_e32 v238, v116, v238
	v_add_f32_e32 v239, v112, v239
	v_add_f32_e32 v240, v124, v240
	v_add_f32_e32 v241, v120, v241
	v_add_f32_e32 v242, v117, v242
	v_add_f32_e32 v243, v113, v243
	v_add_f32_e32 v244, v125, v244
	v_add_f32_e32 v245, v121, v245
	v_add_f32_e32 v246, v118, v246
	v_add_f32_e32 v247, v114, v247
	v_add_f32_e32 v248, v126, v248
	v_add_f32_e32 v249, v122, v249
	v_add_f32_e32 v250, v119, v250
	v_add_f32_e32 v251, v115, v251
	v_add_f32_e32 v252, v127, v252
	v_add_f32_e32 v253, v123, v253
	v_cvt_pk_bf16_f32 v132, v238, v239
	v_cvt_pk_bf16_f32 v133, v240, v241
	v_cvt_pk_bf16_f32 v134, v242, v243
	v_cvt_pk_bf16_f32 v135, v244, v245
	v_cvt_pk_bf16_f32 v136, v246, v247
	v_cvt_pk_bf16_f32 v137, v248, v249
	v_cvt_pk_bf16_f32 v156, v250, v251
	v_cvt_pk_bf16_f32 v157, v252, v253
	global_store_dwordx2 v226, v[132:133], s[2:3] sc1
	v_add_u32_e32 v227, 0x1000, v226
	global_store_dwordx2 v227, v[134:135], s[2:3] sc1
	v_add_u32_e32 v228, 0x2000, v226
	global_store_dwordx2 v228, v[136:137], s[2:3] sc1
	v_add_u32_e32 v227, 0x3000, v226
	global_store_dwordx2 v227, v[156:157], s[2:3] sc1
	v_pk_mul_f32 v[238:239], v[238:239], v[238:239]
	v_pk_mul_f32 v[240:241], v[240:241], v[240:241]
	v_pk_mul_f32 v[242:243], v[242:243], v[242:243]
	v_pk_mul_f32 v[244:245], v[244:245], v[244:245]
	v_pk_mul_f32 v[246:247], v[246:247], v[246:247]
	v_pk_mul_f32 v[248:249], v[248:249], v[248:249]
	v_pk_mul_f32 v[250:251], v[250:251], v[250:251]
	v_pk_mul_f32 v[252:253], v[252:253], v[252:253]
	v_add_f32_e32 v158, v238, v239
	v_add_f32_e32 v159, v242, v243
	v_add_f32_e32 v160, v246, v247
	v_add_f32_e32 v161, v250, v251
	v_add_f32_e32 v158, v240, v158
	v_add_f32_e32 v159, v244, v159
	v_add_f32_e32 v160, v248, v160
	v_add_f32_e32 v161, v252, v161
	v_add_f32_e32 v158, v241, v158
	v_add_f32_e32 v159, v245, v159
	v_add_f32_e32 v160, v249, v160
	v_add_f32_e32 v161, v253, v161
	v_add_f32_dpp v158, v158, v158 row_ror:8 row_mask:0xf bank_mask:0xf bound_ctrl:1
	v_add_f32_dpp v159, v159, v159 row_ror:8 row_mask:0xf bank_mask:0xf bound_ctrl:1
	v_add_f32_dpp v160, v160, v160 row_ror:8 row_mask:0xf bank_mask:0xf bound_ctrl:1
	v_add_f32_dpp v161, v161, v161 row_ror:8 row_mask:0xf bank_mask:0xf bound_ctrl:1
	v_add_f32_dpp v158, v158, v158 row_ror:4 row_mask:0xf bank_mask:0xf bound_ctrl:1
	v_add_f32_dpp v159, v159, v159 row_ror:4 row_mask:0xf bank_mask:0xf bound_ctrl:1
	v_add_f32_dpp v160, v160, v160 row_ror:4 row_mask:0xf bank_mask:0xf bound_ctrl:1
	v_add_f32_dpp v161, v161, v161 row_ror:4 row_mask:0xf bank_mask:0xf bound_ctrl:1
	v_add_f32_dpp v158, v158, v158 row_ror:2 row_mask:0xf bank_mask:0xf bound_ctrl:1
	v_add_f32_dpp v159, v159, v159 row_ror:2 row_mask:0xf bank_mask:0xf bound_ctrl:1
	v_add_f32_dpp v160, v160, v160 row_ror:2 row_mask:0xf bank_mask:0xf bound_ctrl:1
	v_add_f32_dpp v161, v161, v161 row_ror:2 row_mask:0xf bank_mask:0xf bound_ctrl:1
	v_add_f32_dpp v158, v158, v158 row_ror:1 row_mask:0xf bank_mask:0xf bound_ctrl:1
	v_add_f32_dpp v159, v159, v159 row_ror:1 row_mask:0xf bank_mask:0xf bound_ctrl:1
	v_add_f32_dpp v160, v160, v160 row_ror:1 row_mask:0xf bank_mask:0xf bound_ctrl:1
	v_add_f32_dpp v161, v161, v161 row_ror:1 row_mask:0xf bank_mask:0xf bound_ctrl:1
	v_mov_b32_e32 v254, v158
	v_mov_b32_dpp v254, v159 quad_perm:[0,1,2,3] row_mask:0xf bank_mask:0x2
	v_mov_b32_dpp v254, v160 quad_perm:[0,1,2,3] row_mask:0xf bank_mask:0x4
	v_mov_b32_dpp v254, v161 quad_perm:[0,1,2,3] row_mask:0xf bank_mask:0x8
	v_mul_f32_e32 v254, 0x49800000, v254
	v_trunc_f32_e32 v254, v254
	v_mul_f32_e32 v255, 0x2f800000, v254
	v_floor_f32_e32 v255, v255
	v_fmac_f32_e32 v254, 0xcf800000, v255
	v_cvt_u32_f32_e32 v116, v254
	v_cvt_u32_f32_e32 v117, v255
	s_waitcnt vmcnt(42)
; __device__ __forceinline__ float row16_sum(float v) { DPP_ADD(v, 0x128); DPP_ADD(v, 0x124); DPP_ADD(v, 0x122); DPP_ADD(v, 0x121); return v; }
; template <int EPI, int N, int K>
; __device__ __forceinline__ void gemm_phase(const bf16_t* __restrict__ A, const bf16_t* __restrict__ Bt, const EpiArgs ea) {
;     ...
;             const int row = brow + ai * 128 + wr * 64 + m * 16 + fq * 4 + j;
;             const u32x2 x2 = *(const u32x2*)(ea.outb + (size_t)row * DM + c0);
;             float4 xn;
;             xn.x = __builtin_bit_cast(float, x2[0] << 16) + acc[ai][0][m][0][j]; xn.y = __builtin_bit_cast(float, x2[0] & 0xffff0000u) + acc[ai][0][m][1][j];
;             xn.z = __builtin_bit_cast(float, x2[1] << 16) + acc[ai][1][m][0][j]; xn.w = __builtin_bit_cast(float, x2[1] & 0xffff0000u) + acc[ai][1][m][1][j];
;             u32x2 o = {pk2(xn.x, xn.y), pk2(xn.z, xn.w)};
;             st_wt(ea.outb + (size_t)row * DM + c0, o);
;             float ss = xn.x * xn.x + xn.y * xn.y + xn.z * xn.z + xn.w * xn.w;
;             ss = row16_sum(ss);
;             if (fr == 0) __hip_atomic_fetch_add(ea.rowsq_out + row, (rsq_t)(ss * RSQ_SCALE), __ATOMIC_RELAXED, __HIP_MEMORY_SCOPE_AGENT);
	v_lshlrev_b32_e32 v238, 16, v170
	v_and_b32_e32 v239, 0xffff0000, v170
	v_lshlrev_b32_e32 v240, 16, v171
	v_and_b32_e32 v241, 0xffff0000, v171
	v_lshlrev_b32_e32 v242, 16, v172
	v_and_b32_e32 v243, 0xffff0000, v172
	v_lshlrev_b32_e32 v244, 16, v173
	v_and_b32_e32 v245, 0xffff0000, v173
	v_lshlrev_b32_e32 v246, 16, v174
	v_and_b32_e32 v247, 0xffff0000, v174
	v_lshlrev_b32_e32 v248, 16, v175
	v_and_b32_e32 v249, 0xffff0000, v175
	v_lshlrev_b32_e32 v250, 16, v176
	v_and_b32_e32 v251, 0xffff0000, v176
	v_lshlrev_b32_e32 v252, 16, v177
	v_and_b32_e32 v253, 0xffff0000, v177
	v_add_f32_e32 v238, v100, v238
	v_add_f32_e32 v239, v96, v239
	v_add_f32_e32 v240, v108, v240
	v_add_f32_e32 v241, v104, v241
	v_add_f32_e32 v242, v101, v242
	v_add_f32_e32 v243, v97, v243
	v_add_f32_e32 v244, v109, v244
	v_add_f32_e32 v245, v105, v245
	v_add_f32_e32 v246, v102, v246
	v_add_f32_e32 v247, v98, v247
	v_add_f32_e32 v248, v110, v248
	v_add_f32_e32 v249, v106, v249
	v_add_f32_e32 v250, v103, v250
	v_add_f32_e32 v251, v99, v251
	v_add_f32_e32 v252, v111, v252
	v_add_f32_e32 v253, v107, v253
	v_cvt_pk_bf16_f32 v132, v238, v239
	v_cvt_pk_bf16_f32 v133, v240, v241
	v_cvt_pk_bf16_f32 v134, v242, v243
	v_cvt_pk_bf16_f32 v135, v244, v245
	v_cvt_pk_bf16_f32 v136, v246, v247
	v_cvt_pk_bf16_f32 v137, v248, v249
	v_cvt_pk_bf16_f32 v156, v250, v251
	v_cvt_pk_bf16_f32 v157, v252, v253
	v_add_u32_e32 v228, 0x10000, v226
	global_store_dwordx2 v228, v[132:133], s[2:3] sc1
	v_add_u32_e32 v227, 0x11000, v226
	global_store_dwordx2 v227, v[134:135], s[2:3] sc1
	v_add_u32_e32 v228, 0x12000, v226
	global_store_dwordx2 v228, v[136:137], s[2:3] sc1
	v_add_u32_e32 v227, 0x13000, v226
	global_store_dwordx2 v227, v[156:157], s[2:3] sc1
	v_pk_mul_f32 v[238:239], v[238:239], v[238:239]
	v_pk_mul_f32 v[240:241], v[240:241], v[240:241]
	v_pk_mul_f32 v[242:243], v[242:243], v[242:243]
	v_pk_mul_f32 v[244:245], v[244:245], v[244:245]
	v_pk_mul_f32 v[246:247], v[246:247], v[246:247]
	v_pk_mul_f32 v[248:249], v[248:249], v[248:249]
	v_pk_mul_f32 v[250:251], v[250:251], v[250:251]
	v_pk_mul_f32 v[252:253], v[252:253], v[252:253]
	v_add_f32_e32 v158, v238, v239
	v_add_f32_e32 v159, v242, v243
	v_add_f32_e32 v160, v246, v247
	v_add_f32_e32 v161, v250, v251
	v_add_f32_e32 v158, v240, v158
	v_add_f32_e32 v159, v244, v159
	v_add_f32_e32 v160, v248, v160
	v_add_f32_e32 v161, v252, v161
	v_add_f32_e32 v158, v241, v158
	v_add_f32_e32 v159, v245, v159
	v_add_f32_e32 v160, v249, v160
	v_add_f32_e32 v161, v253, v161
	v_add_f32_dpp v158, v158, v158 row_ror:8 row_mask:0xf bank_mask:0xf bound_ctrl:1
	v_add_f32_dpp v159, v159, v159 row_ror:8 row_mask:0xf bank_mask:0xf bound_ctrl:1
	v_add_f32_dpp v160, v160, v160 row_ror:8 row_mask:0xf bank_mask:0xf bound_ctrl:1
	v_add_f32_dpp v161, v161, v161 row_ror:8 row_mask:0xf bank_mask:0xf bound_ctrl:1
	v_add_f32_dpp v158, v158, v158 row_ror:4 row_mask:0xf bank_mask:0xf bound_ctrl:1
	v_add_f32_dpp v159, v159, v159 row_ror:4 row_mask:0xf bank_mask:0xf bound_ctrl:1
	v_add_f32_dpp v160, v160, v160 row_ror:4 row_mask:0xf bank_mask:0xf bound_ctrl:1
	v_add_f32_dpp v161, v161, v161 row_ror:4 row_mask:0xf bank_mask:0xf bound_ctrl:1
	v_add_f32_dpp v158, v158, v158 row_ror:2 row_mask:0xf bank_mask:0xf bound_ctrl:1
	v_add_f32_dpp v159, v159, v159 row_ror:2 row_mask:0xf bank_mask:0xf bound_ctrl:1
	v_add_f32_dpp v160, v160, v160 row_ror:2 row_mask:0xf bank_mask:0xf bound_ctrl:1
	v_add_f32_dpp v161, v161, v161 row_ror:2 row_mask:0xf bank_mask:0xf bound_ctrl:1
	v_add_f32_dpp v158, v158, v158 row_ror:1 row_mask:0xf bank_mask:0xf bound_ctrl:1
	v_add_f32_dpp v159, v159, v159 row_ror:1 row_mask:0xf bank_mask:0xf bound_ctrl:1
	v_add_f32_dpp v160, v160, v160 row_ror:1 row_mask:0xf bank_mask:0xf bound_ctrl:1
	v_add_f32_dpp v161, v161, v161 row_ror:1 row_mask:0xf bank_mask:0xf bound_ctrl:1
	v_mov_b32_e32 v254, v158
	v_mov_b32_dpp v254, v159 quad_perm:[0,1,2,3] row_mask:0xf bank_mask:0x2
	v_mov_b32_dpp v254, v160 quad_perm:[0,1,2,3] row_mask:0xf bank_mask:0x4
	v_mov_b32_dpp v254, v161 quad_perm:[0,1,2,3] row_mask:0xf bank_mask:0x8
	v_mul_f32_e32 v254, 0x49800000, v254
	v_trunc_f32_e32 v254, v254
	v_mul_f32_e32 v255, 0x2f800000, v254
	v_floor_f32_e32 v255, v255
	v_fmac_f32_e32 v254, 0xcf800000, v255
	v_cvt_u32_f32_e32 v100, v254
	v_cvt_u32_f32_e32 v101, v255
	s_waitcnt vmcnt(42)
; __device__ __forceinline__ float row16_sum(float v) { DPP_ADD(v, 0x128); DPP_ADD(v, 0x124); DPP_ADD(v, 0x122); DPP_ADD(v, 0x121); return v; }
; template <int EPI, int N, int K>
; __device__ __forceinline__ void gemm_phase(const bf16_t* __restrict__ A, const bf16_t* __restrict__ Bt, const EpiArgs ea) {
;     ...
;             const int row = brow + ai * 128 + wr * 64 + m * 16 + fq * 4 + j;
;             const u32x2 x2 = *(const u32x2*)(ea.outb + (size_t)row * DM + c0);
;             float4 xn;
;             xn.x = __builtin_bit_cast(float, x2[0] << 16) + acc[ai][0][m][0][j]; xn.y = __builtin_bit_cast(float, x2[0] & 0xffff0000u) + acc[ai][0][m][1][j];
;             xn.z = __builtin_bit_cast(float, x2[1] << 16) + acc[ai][1][m][0][j]; xn.w = __builtin_bit_cast(float, x2[1] & 0xffff0000u) + acc[ai][1][m][1][j];
;             u32x2 o = {pk2(xn.x, xn.y), pk2(xn.z, xn.w)};
;             st_wt(ea.outb + (size_t)row * DM + c0, o);
;             float ss = xn.x * xn.x + xn.y * xn.y + xn.z * xn.z + xn.w * xn.w;
;             ss = row16_sum(ss);
;             if (fr == 0) __hip_atomic_fetch_add(ea.rowsq_out + row, (rsq_t)(ss * RSQ_SCALE), __ATOMIC_RELAXED, __HIP_MEMORY_SCOPE_AGENT);
	v_lshlrev_b32_e32 v238, 16, v178
	v_and_b32_e32 v239, 0xffff0000, v178
	v_lshlrev_b32_e32 v240, 16, v179
	v_and_b32_e32 v241, 0xffff0000, v179
	v_lshlrev_b32_e32 v242, 16, v180
	v_and_b32_e32 v243, 0xffff0000, v180
	v_lshlrev_b32_e32 v244, 16, v181
	v_and_b32_e32 v245, 0xffff0000, v181
	v_lshlrev_b32_e32 v246, 16, v182
	v_and_b32_e32 v247, 0xffff0000, v182
	v_lshlrev_b32_e32 v248, 16, v183
	v_and_b32_e32 v249, 0xffff0000, v183
	v_lshlrev_b32_e32 v250, 16, v184
	v_and_b32_e32 v251, 0xffff0000, v184
	v_lshlrev_b32_e32 v252, 16, v185
	v_and_b32_e32 v253, 0xffff0000, v185
	v_add_f32_e32 v238, v84, v238
	v_add_f32_e32 v239, v80, v239
	v_add_f32_e32 v240, v92, v240
	v_add_f32_e32 v241, v88, v241
	v_add_f32_e32 v242, v85, v242
	v_add_f32_e32 v243, v81, v243
	v_add_f32_e32 v244, v93, v244
	v_add_f32_e32 v245, v89, v245
	v_add_f32_e32 v246, v86, v246
	v_add_f32_e32 v247, v82, v247
	v_add_f32_e32 v248, v94, v248
	v_add_f32_e32 v249, v90, v249
	v_add_f32_e32 v250, v87, v250
	v_add_f32_e32 v251, v83, v251
	v_add_f32_e32 v252, v95, v252
	v_add_f32_e32 v253, v91, v253
	v_cvt_pk_bf16_f32 v132, v238, v239
	v_cvt_pk_bf16_f32 v133, v240, v241
	v_cvt_pk_bf16_f32 v134, v242, v243
	v_cvt_pk_bf16_f32 v135, v244, v245
	v_cvt_pk_bf16_f32 v136, v246, v247
	v_cvt_pk_bf16_f32 v137, v248, v249
	v_cvt_pk_bf16_f32 v156, v250, v251
	v_cvt_pk_bf16_f32 v157, v252, v253
	v_add_u32_e32 v228, 0x20000, v226
	global_store_dwordx2 v228, v[132:133], s[2:3] sc1
	v_add_u32_e32 v227, 0x21000, v226
	global_store_dwordx2 v227, v[134:135], s[2:3] sc1
	v_add_u32_e32 v228, 0x22000, v226
	global_store_dwordx2 v228, v[136:137], s[2:3] sc1
	v_add_u32_e32 v227, 0x23000, v226
	global_store_dwordx2 v227, v[156:157], s[2:3] sc1
	v_pk_mul_f32 v[238:239], v[238:239], v[238:239]
	v_pk_mul_f32 v[240:241], v[240:241], v[240:241]
	v_pk_mul_f32 v[242:243], v[242:243], v[242:243]
	v_pk_mul_f32 v[244:245], v[244:245], v[244:245]
	v_pk_mul_f32 v[246:247], v[246:247], v[246:247]
	v_pk_mul_f32 v[248:249], v[248:249], v[248:249]
	v_pk_mul_f32 v[250:251], v[250:251], v[250:251]
	v_pk_mul_f32 v[252:253], v[252:253], v[252:253]
	v_add_f32_e32 v158, v238, v239
	v_add_f32_e32 v159, v242, v243
	v_add_f32_e32 v160, v246, v247
	v_add_f32_e32 v161, v250, v251
	v_add_f32_e32 v158, v240, v158
	v_add_f32_e32 v159, v244, v159
	v_add_f32_e32 v160, v248, v160
	v_add_f32_e32 v161, v252, v161
	v_add_f32_e32 v158, v241, v158
	v_add_f32_e32 v159, v245, v159
	v_add_f32_e32 v160, v249, v160
	v_add_f32_e32 v161, v253, v161
	v_add_f32_dpp v158, v158, v158 row_ror:8 row_mask:0xf bank_mask:0xf bound_ctrl:1
	v_add_f32_dpp v159, v159, v159 row_ror:8 row_mask:0xf bank_mask:0xf bound_ctrl:1
	v_add_f32_dpp v160, v160, v160 row_ror:8 row_mask:0xf bank_mask:0xf bound_ctrl:1
	v_add_f32_dpp v161, v161, v161 row_ror:8 row_mask:0xf bank_mask:0xf bound_ctrl:1
	v_add_f32_dpp v158, v158, v158 row_ror:4 row_mask:0xf bank_mask:0xf bound_ctrl:1
	v_add_f32_dpp v159, v159, v159 row_ror:4 row_mask:0xf bank_mask:0xf bound_ctrl:1
	v_add_f32_dpp v160, v160, v160 row_ror:4 row_mask:0xf bank_mask:0xf bound_ctrl:1
	v_add_f32_dpp v161, v161, v161 row_ror:4 row_mask:0xf bank_mask:0xf bound_ctrl:1
	v_add_f32_dpp v158, v158, v158 row_ror:2 row_mask:0xf bank_mask:0xf bound_ctrl:1
	v_add_f32_dpp v159, v159, v159 row_ror:2 row_mask:0xf bank_mask:0xf bound_ctrl:1
	v_add_f32_dpp v160, v160, v160 row_ror:2 row_mask:0xf bank_mask:0xf bound_ctrl:1
	v_add_f32_dpp v161, v161, v161 row_ror:2 row_mask:0xf bank_mask:0xf bound_ctrl:1
	v_add_f32_dpp v158, v158, v158 row_ror:1 row_mask:0xf bank_mask:0xf bound_ctrl:1
	v_add_f32_dpp v159, v159, v159 row_ror:1 row_mask:0xf bank_mask:0xf bound_ctrl:1
	v_add_f32_dpp v160, v160, v160 row_ror:1 row_mask:0xf bank_mask:0xf bound_ctrl:1
	v_add_f32_dpp v161, v161, v161 row_ror:1 row_mask:0xf bank_mask:0xf bound_ctrl:1
	v_mov_b32_e32 v254, v158
	v_mov_b32_dpp v254, v159 quad_perm:[0,1,2,3] row_mask:0xf bank_mask:0x2
	v_mov_b32_dpp v254, v160 quad_perm:[0,1,2,3] row_mask:0xf bank_mask:0x4
	v_mov_b32_dpp v254, v161 quad_perm:[0,1,2,3] row_mask:0xf bank_mask:0x8
	v_mul_f32_e32 v254, 0x49800000, v254
	v_trunc_f32_e32 v254, v254
	v_mul_f32_e32 v255, 0x2f800000, v254
	v_floor_f32_e32 v255, v255
	v_fmac_f32_e32 v254, 0xcf800000, v255
	v_cvt_u32_f32_e32 v84, v254
	v_cvt_u32_f32_e32 v85, v255
	s_waitcnt vmcnt(42)
; __device__ __forceinline__ float row16_sum(float v) { DPP_ADD(v, 0x128); DPP_ADD(v, 0x124); DPP_ADD(v, 0x122); DPP_ADD(v, 0x121); return v; }
; template <int EPI, int N, int K>
; __device__ __forceinline__ void gemm_phase(const bf16_t* __restrict__ A, const bf16_t* __restrict__ Bt, const EpiArgs ea) {
;     ...
;             const int row = brow + ai * 128 + wr * 64 + m * 16 + fq * 4 + j;
;             const u32x2 x2 = *(const u32x2*)(ea.outb + (size_t)row * DM + c0);
;             float4 xn;
;             xn.x = __builtin_bit_cast(float, x2[0] << 16) + acc[ai][0][m][0][j]; xn.y = __builtin_bit_cast(float, x2[0] & 0xffff0000u) + acc[ai][0][m][1][j];
;             xn.z = __builtin_bit_cast(float, x2[1] << 16) + acc[ai][1][m][0][j]; xn.w = __builtin_bit_cast(float, x2[1] & 0xffff0000u) + acc[ai][1][m][1][j];
;             u32x2 o = {pk2(xn.x, xn.y), pk2(xn.z, xn.w)};
;             st_wt(ea.outb + (size_t)row * DM + c0, o);
;             float ss = xn.x * xn.x + xn.y * xn.y + xn.z * xn.z + xn.w * xn.w;
;             ss = row16_sum(ss);
;             if (fr == 0) __hip_atomic_fetch_add(ea.rowsq_out + row, (rsq_t)(ss * RSQ_SCALE), __ATOMIC_RELAXED, __HIP_MEMORY_SCOPE_AGENT);
	v_lshlrev_b32_e32 v238, 16, v186
	v_and_b32_e32 v239, 0xffff0000, v186
	v_lshlrev_b32_e32 v240, 16, v187
	v_and_b32_e32 v241, 0xffff0000, v187
	v_lshlrev_b32_e32 v242, 16, v188
	v_and_b32_e32 v243, 0xffff0000, v188
	v_lshlrev_b32_e32 v244, 16, v189
	v_and_b32_e32 v245, 0xffff0000, v189
	v_lshlrev_b32_e32 v246, 16, v190
	v_and_b32_e32 v247, 0xffff0000, v190
	v_lshlrev_b32_e32 v248, 16, v191
	v_and_b32_e32 v249, 0xffff0000, v191
	v_lshlrev_b32_e32 v250, 16, v192
	v_and_b32_e32 v251, 0xffff0000, v192
	v_lshlrev_b32_e32 v252, 16, v193
	v_and_b32_e32 v253, 0xffff0000, v193
	v_add_f32_e32 v238, v68, v238
	v_add_f32_e32 v239, v64, v239
	v_add_f32_e32 v240, v76, v240
	v_add_f32_e32 v241, v72, v241
	v_add_f32_e32 v242, v69, v242
	v_add_f32_e32 v243, v65, v243
	v_add_f32_e32 v244, v77, v244
	v_add_f32_e32 v245, v73, v245
	v_add_f32_e32 v246, v70, v246
	v_add_f32_e32 v247, v66, v247
	v_add_f32_e32 v248, v78, v248
	v_add_f32_e32 v249, v74, v249
	v_add_f32_e32 v250, v71, v250
	v_add_f32_e32 v251, v67, v251
	v_add_f32_e32 v252, v79, v252
	v_add_f32_e32 v253, v75, v253
	v_cvt_pk_bf16_f32 v132, v238, v239
	v_cvt_pk_bf16_f32 v133, v240, v241
	v_cvt_pk_bf16_f32 v134, v242, v243
	v_cvt_pk_bf16_f32 v135, v244, v245
	v_cvt_pk_bf16_f32 v136, v246, v247
	v_cvt_pk_bf16_f32 v137, v248, v249
	v_cvt_pk_bf16_f32 v156, v250, v251
	v_cvt_pk_bf16_f32 v157, v252, v253
	v_add_u32_e32 v228, 0x30000, v226
	global_store_dwordx2 v228, v[132:133], s[2:3] sc1
	v_add_u32_e32 v227, 0x31000, v226
	global_store_dwordx2 v227, v[134:135], s[2:3] sc1
	v_add_u32_e32 v228, 0x32000, v226
	global_store_dwordx2 v228, v[136:137], s[2:3] sc1
	v_add_u32_e32 v227, 0x33000, v226
	global_store_dwordx2 v227, v[156:157], s[2:3] sc1
	v_pk_mul_f32 v[238:239], v[238:239], v[238:239]
	v_pk_mul_f32 v[240:241], v[240:241], v[240:241]
	v_pk_mul_f32 v[242:243], v[242:243], v[242:243]
	v_pk_mul_f32 v[244:245], v[244:245], v[244:245]
	v_pk_mul_f32 v[246:247], v[246:247], v[246:247]
	v_pk_mul_f32 v[248:249], v[248:249], v[248:249]
	v_pk_mul_f32 v[250:251], v[250:251], v[250:251]
	v_pk_mul_f32 v[252:253], v[252:253], v[252:253]
	v_add_f32_e32 v158, v238, v239
	v_add_f32_e32 v159, v242, v243
	v_add_f32_e32 v160, v246, v247
	v_add_f32_e32 v161, v250, v251
	v_add_f32_e32 v158, v240, v158
	v_add_f32_e32 v159, v244, v159
	v_add_f32_e32 v160, v248, v160
	v_add_f32_e32 v161, v252, v161
	v_add_f32_e32 v158, v241, v158
	v_add_f32_e32 v159, v245, v159
	v_add_f32_e32 v160, v249, v160
	v_add_f32_e32 v161, v253, v161
	v_add_f32_dpp v158, v158, v158 row_ror:8 row_mask:0xf bank_mask:0xf bound_ctrl:1
	v_add_f32_dpp v159, v159, v159 row_ror:8 row_mask:0xf bank_mask:0xf bound_ctrl:1
	v_add_f32_dpp v160, v160, v160 row_ror:8 row_mask:0xf bank_mask:0xf bound_ctrl:1
	v_add_f32_dpp v161, v161, v161 row_ror:8 row_mask:0xf bank_mask:0xf bound_ctrl:1
	v_add_f32_dpp v158, v158, v158 row_ror:4 row_mask:0xf bank_mask:0xf bound_ctrl:1
	v_add_f32_dpp v159, v159, v159 row_ror:4 row_mask:0xf bank_mask:0xf bound_ctrl:1
	v_add_f32_dpp v160, v160, v160 row_ror:4 row_mask:0xf bank_mask:0xf bound_ctrl:1
	v_add_f32_dpp v161, v161, v161 row_ror:4 row_mask:0xf bank_mask:0xf bound_ctrl:1
	v_add_f32_dpp v158, v158, v158 row_ror:2 row_mask:0xf bank_mask:0xf bound_ctrl:1
	v_add_f32_dpp v159, v159, v159 row_ror:2 row_mask:0xf bank_mask:0xf bound_ctrl:1
	v_add_f32_dpp v160, v160, v160 row_ror:2 row_mask:0xf bank_mask:0xf bound_ctrl:1
	v_add_f32_dpp v161, v161, v161 row_ror:2 row_mask:0xf bank_mask:0xf bound_ctrl:1
	v_add_f32_dpp v158, v158, v158 row_ror:1 row_mask:0xf bank_mask:0xf bound_ctrl:1
	v_add_f32_dpp v159, v159, v159 row_ror:1 row_mask:0xf bank_mask:0xf bound_ctrl:1
	v_add_f32_dpp v160, v160, v160 row_ror:1 row_mask:0xf bank_mask:0xf bound_ctrl:1
	v_add_f32_dpp v161, v161, v161 row_ror:1 row_mask:0xf bank_mask:0xf bound_ctrl:1
	v_mov_b32_e32 v254, v158
	v_mov_b32_dpp v254, v159 quad_perm:[0,1,2,3] row_mask:0xf bank_mask:0x2
	v_mov_b32_dpp v254, v160 quad_perm:[0,1,2,3] row_mask:0xf bank_mask:0x4
	v_mov_b32_dpp v254, v161 quad_perm:[0,1,2,3] row_mask:0xf bank_mask:0x8
	v_mul_f32_e32 v254, 0x49800000, v254
	v_trunc_f32_e32 v254, v254
	v_mul_f32_e32 v255, 0x2f800000, v254
	v_floor_f32_e32 v255, v255
	v_fmac_f32_e32 v254, 0xcf800000, v255
	v_cvt_u32_f32_e32 v68, v254
	v_cvt_u32_f32_e32 v69, v255
	s_waitcnt vmcnt(42)
; __device__ __forceinline__ float row16_sum(float v) { DPP_ADD(v, 0x128); DPP_ADD(v, 0x124); DPP_ADD(v, 0x122); DPP_ADD(v, 0x121); return v; }
; template <int EPI, int N, int K>
; __device__ __forceinline__ void gemm_phase(const bf16_t* __restrict__ A, const bf16_t* __restrict__ Bt, const EpiArgs ea) {
;     ...
;             const int row = brow + ai * 128 + wr * 64 + m * 16 + fq * 4 + j;
;             const u32x2 x2 = *(const u32x2*)(ea.outb + (size_t)row * DM + c0);
;             float4 xn;
;             xn.x = __builtin_bit_cast(float, x2[0] << 16) + acc[ai][0][m][0][j]; xn.y = __builtin_bit_cast(float, x2[0] & 0xffff0000u) + acc[ai][0][m][1][j];
;             xn.z = __builtin_bit_cast(float, x2[1] << 16) + acc[ai][1][m][0][j]; xn.w = __builtin_bit_cast(float, x2[1] & 0xffff0000u) + acc[ai][1][m][1][j];
;             u32x2 o = {pk2(xn.x, xn.y), pk2(xn.z, xn.w)};
;             st_wt(ea.outb + (size_t)row * DM + c0, o);
;             float ss = xn.x * xn.x + xn.y * xn.y + xn.z * xn.z + xn.w * xn.w;
;             ss = row16_sum(ss);
;             if (fr == 0) __hip_atomic_fetch_add(ea.rowsq_out + row, (rsq_t)(ss * RSQ_SCALE), __ATOMIC_RELAXED, __HIP_MEMORY_SCOPE_AGENT);
	v_lshlrev_b32_e32 v238, 16, v194
	v_and_b32_e32 v239, 0xffff0000, v194
	v_lshlrev_b32_e32 v240, 16, v195
	v_and_b32_e32 v241, 0xffff0000, v195
	v_lshlrev_b32_e32 v242, 16, v196
	v_and_b32_e32 v243, 0xffff0000, v196
	v_lshlrev_b32_e32 v244, 16, v197
	v_and_b32_e32 v245, 0xffff0000, v197
	v_lshlrev_b32_e32 v246, 16, v198
	v_and_b32_e32 v247, 0xffff0000, v198
	v_lshlrev_b32_e32 v248, 16, v199
	v_and_b32_e32 v249, 0xffff0000, v199
	v_lshlrev_b32_e32 v250, 16, v200
	v_and_b32_e32 v251, 0xffff0000, v200
	v_lshlrev_b32_e32 v252, 16, v201
	v_and_b32_e32 v253, 0xffff0000, v201
	v_add_f32_e32 v238, v52, v238
	v_add_f32_e32 v239, v48, v239
	v_add_f32_e32 v240, v60, v240
	v_add_f32_e32 v241, v56, v241
	v_add_f32_e32 v242, v53, v242
	v_add_f32_e32 v243, v49, v243
	v_add_f32_e32 v244, v61, v244
	v_add_f32_e32 v245, v57, v245
	v_add_f32_e32 v246, v54, v246
	v_add_f32_e32 v247, v50, v247
	v_add_f32_e32 v248, v62, v248
	v_add_f32_e32 v249, v58, v249
	v_add_f32_e32 v250, v55, v250
	v_add_f32_e32 v251, v51, v251
	v_add_f32_e32 v252, v63, v252
	v_add_f32_e32 v253, v59, v253
	v_cvt_pk_bf16_f32 v132, v238, v239
	v_cvt_pk_bf16_f32 v133, v240, v241
	v_cvt_pk_bf16_f32 v134, v242, v243
	v_cvt_pk_bf16_f32 v135, v244, v245
	v_cvt_pk_bf16_f32 v136, v246, v247
	v_cvt_pk_bf16_f32 v137, v248, v249
	v_cvt_pk_bf16_f32 v156, v250, v251
	v_cvt_pk_bf16_f32 v157, v252, v253
	v_add_u32_e32 v228, 0x80000, v226
	global_store_dwordx2 v228, v[132:133], s[2:3] sc1
	v_add_u32_e32 v227, 0x81000, v226
	global_store_dwordx2 v227, v[134:135], s[2:3] sc1
	v_add_u32_e32 v228, 0x82000, v226
	global_store_dwordx2 v228, v[136:137], s[2:3] sc1
	v_add_u32_e32 v227, 0x83000, v226
	global_store_dwordx2 v227, v[156:157], s[2:3] sc1
	v_pk_mul_f32 v[238:239], v[238:239], v[238:239]
	v_pk_mul_f32 v[240:241], v[240:241], v[240:241]
	v_pk_mul_f32 v[242:243], v[242:243], v[242:243]
	v_pk_mul_f32 v[244:245], v[244:245], v[244:245]
	v_pk_mul_f32 v[246:247], v[246:247], v[246:247]
	v_pk_mul_f32 v[248:249], v[248:249], v[248:249]
	v_pk_mul_f32 v[250:251], v[250:251], v[250:251]
	v_pk_mul_f32 v[252:253], v[252:253], v[252:253]
	v_add_f32_e32 v158, v238, v239
	v_add_f32_e32 v159, v242, v243
	v_add_f32_e32 v160, v246, v247
	v_add_f32_e32 v161, v250, v251
	v_add_f32_e32 v158, v240, v158
	v_add_f32_e32 v159, v244, v159
	v_add_f32_e32 v160, v248, v160
	v_add_f32_e32 v161, v252, v161
	v_add_f32_e32 v158, v241, v158
	v_add_f32_e32 v159, v245, v159
	v_add_f32_e32 v160, v249, v160
	v_add_f32_e32 v161, v253, v161
	v_add_f32_dpp v158, v158, v158 row_ror:8 row_mask:0xf bank_mask:0xf bound_ctrl:1
	v_add_f32_dpp v159, v159, v159 row_ror:8 row_mask:0xf bank_mask:0xf bound_ctrl:1
	v_add_f32_dpp v160, v160, v160 row_ror:8 row_mask:0xf bank_mask:0xf bound_ctrl:1
	v_add_f32_dpp v161, v161, v161 row_ror:8 row_mask:0xf bank_mask:0xf bound_ctrl:1
	v_add_f32_dpp v158, v158, v158 row_ror:4 row_mask:0xf bank_mask:0xf bound_ctrl:1
	v_add_f32_dpp v159, v159, v159 row_ror:4 row_mask:0xf bank_mask:0xf bound_ctrl:1
	v_add_f32_dpp v160, v160, v160 row_ror:4 row_mask:0xf bank_mask:0xf bound_ctrl:1
	v_add_f32_dpp v161, v161, v161 row_ror:4 row_mask:0xf bank_mask:0xf bound_ctrl:1
	v_add_f32_dpp v158, v158, v158 row_ror:2 row_mask:0xf bank_mask:0xf bound_ctrl:1
	v_add_f32_dpp v159, v159, v159 row_ror:2 row_mask:0xf bank_mask:0xf bound_ctrl:1
	v_add_f32_dpp v160, v160, v160 row_ror:2 row_mask:0xf bank_mask:0xf bound_ctrl:1
	v_add_f32_dpp v161, v161, v161 row_ror:2 row_mask:0xf bank_mask:0xf bound_ctrl:1
	v_add_f32_dpp v158, v158, v158 row_ror:1 row_mask:0xf bank_mask:0xf bound_ctrl:1
	v_add_f32_dpp v159, v159, v159 row_ror:1 row_mask:0xf bank_mask:0xf bound_ctrl:1
	v_add_f32_dpp v160, v160, v160 row_ror:1 row_mask:0xf bank_mask:0xf bound_ctrl:1
	v_add_f32_dpp v161, v161, v161 row_ror:1 row_mask:0xf bank_mask:0xf bound_ctrl:1
	v_mov_b32_e32 v254, v158
	v_mov_b32_dpp v254, v159 quad_perm:[0,1,2,3] row_mask:0xf bank_mask:0x2
	v_mov_b32_dpp v254, v160 quad_perm:[0,1,2,3] row_mask:0xf bank_mask:0x4
	v_mov_b32_dpp v254, v161 quad_perm:[0,1,2,3] row_mask:0xf bank_mask:0x8
	v_mul_f32_e32 v254, 0x49800000, v254
	v_trunc_f32_e32 v254, v254
	v_mul_f32_e32 v255, 0x2f800000, v254
	v_floor_f32_e32 v255, v255
	v_fmac_f32_e32 v254, 0xcf800000, v255
	v_cvt_u32_f32_e32 v52, v254
	v_cvt_u32_f32_e32 v53, v255
	s_waitcnt vmcnt(42)
; __device__ __forceinline__ float row16_sum(float v) { DPP_ADD(v, 0x128); DPP_ADD(v, 0x124); DPP_ADD(v, 0x122); DPP_ADD(v, 0x121); return v; }
; template <int EPI, int N, int K>
; __device__ __forceinline__ void gemm_phase(const bf16_t* __restrict__ A, const bf16_t* __restrict__ Bt, const EpiArgs ea) {
;     ...
;             const int row = brow + ai * 128 + wr * 64 + m * 16 + fq * 4 + j;
;             const u32x2 x2 = *(const u32x2*)(ea.outb + (size_t)row * DM + c0);
;             float4 xn;
;             xn.x = __builtin_bit_cast(float, x2[0] << 16) + acc[ai][0][m][0][j]; xn.y = __builtin_bit_cast(float, x2[0] & 0xffff0000u) + acc[ai][0][m][1][j];
;             xn.z = __builtin_bit_cast(float, x2[1] << 16) + acc[ai][1][m][0][j]; xn.w = __builtin_bit_cast(float, x2[1] & 0xffff0000u) + acc[ai][1][m][1][j];
;             u32x2 o = {pk2(xn.x, xn.y), pk2(xn.z, xn.w)};
;             st_wt(ea.outb + (size_t)row * DM + c0, o);
;             float ss = xn.x * xn.x + xn.y * xn.y + xn.z * xn.z + xn.w * xn.w;
;             ss = row16_sum(ss);
;             if (fr == 0) __hip_atomic_fetch_add(ea.rowsq_out + row, (rsq_t)(ss * RSQ_SCALE), __ATOMIC_RELAXED, __HIP_MEMORY_SCOPE_AGENT);
	v_lshlrev_b32_e32 v238, 16, v202
	v_and_b32_e32 v239, 0xffff0000, v202
	v_lshlrev_b32_e32 v240, 16, v203
	v_and_b32_e32 v241, 0xffff0000, v203
	v_lshlrev_b32_e32 v242, 16, v204
	v_and_b32_e32 v243, 0xffff0000, v204
	v_lshlrev_b32_e32 v244, 16, v205
	v_and_b32_e32 v245, 0xffff0000, v205
	v_lshlrev_b32_e32 v246, 16, v206
	v_and_b32_e32 v247, 0xffff0000, v206
	v_lshlrev_b32_e32 v248, 16, v207
	v_and_b32_e32 v249, 0xffff0000, v207
	v_lshlrev_b32_e32 v250, 16, v208
	v_and_b32_e32 v251, 0xffff0000, v208
	v_lshlrev_b32_e32 v252, 16, v209
	v_and_b32_e32 v253, 0xffff0000, v209
	v_add_f32_e32 v238, v36, v238
	v_add_f32_e32 v239, v32, v239
	v_add_f32_e32 v240, v44, v240
	v_add_f32_e32 v241, v40, v241
	v_add_f32_e32 v242, v37, v242
	v_add_f32_e32 v243, v33, v243
	v_add_f32_e32 v244, v45, v244
	v_add_f32_e32 v245, v41, v245
	v_add_f32_e32 v246, v38, v246
	v_add_f32_e32 v247, v34, v247
	v_add_f32_e32 v248, v46, v248
	v_add_f32_e32 v249, v42, v249
	v_add_f32_e32 v250, v39, v250
	v_add_f32_e32 v251, v35, v251
	v_add_f32_e32 v252, v47, v252
	v_add_f32_e32 v253, v43, v253
	v_cvt_pk_bf16_f32 v132, v238, v239
	v_cvt_pk_bf16_f32 v133, v240, v241
	v_cvt_pk_bf16_f32 v134, v242, v243
	v_cvt_pk_bf16_f32 v135, v244, v245
	v_cvt_pk_bf16_f32 v136, v246, v247
	v_cvt_pk_bf16_f32 v137, v248, v249
	v_cvt_pk_bf16_f32 v156, v250, v251
	v_cvt_pk_bf16_f32 v157, v252, v253
	v_add_u32_e32 v228, 0x90000, v226
	global_store_dwordx2 v228, v[132:133], s[2:3] sc1
	v_add_u32_e32 v227, 0x91000, v226
	global_store_dwordx2 v227, v[134:135], s[2:3] sc1
	v_add_u32_e32 v228, 0x92000, v226
	global_store_dwordx2 v228, v[136:137], s[2:3] sc1
	v_add_u32_e32 v227, 0x93000, v226
	global_store_dwordx2 v227, v[156:157], s[2:3] sc1
	v_pk_mul_f32 v[238:239], v[238:239], v[238:239]
	v_pk_mul_f32 v[240:241], v[240:241], v[240:241]
	v_pk_mul_f32 v[242:243], v[242:243], v[242:243]
	v_pk_mul_f32 v[244:245], v[244:245], v[244:245]
	v_pk_mul_f32 v[246:247], v[246:247], v[246:247]
	v_pk_mul_f32 v[248:249], v[248:249], v[248:249]
	v_pk_mul_f32 v[250:251], v[250:251], v[250:251]
	v_pk_mul_f32 v[252:253], v[252:253], v[252:253]
	v_add_f32_e32 v158, v238, v239
	v_add_f32_e32 v159, v242, v243
	v_add_f32_e32 v160, v246, v247
	v_add_f32_e32 v161, v250, v251
	v_add_f32_e32 v158, v240, v158
	v_add_f32_e32 v159, v244, v159
	v_add_f32_e32 v160, v248, v160
	v_add_f32_e32 v161, v252, v161
	v_add_f32_e32 v158, v241, v158
	v_add_f32_e32 v159, v245, v159
	v_add_f32_e32 v160, v249, v160
	v_add_f32_e32 v161, v253, v161
	v_add_f32_dpp v158, v158, v158 row_ror:8 row_mask:0xf bank_mask:0xf bound_ctrl:1
	v_add_f32_dpp v159, v159, v159 row_ror:8 row_mask:0xf bank_mask:0xf bound_ctrl:1
	v_add_f32_dpp v160, v160, v160 row_ror:8 row_mask:0xf bank_mask:0xf bound_ctrl:1
	v_add_f32_dpp v161, v161, v161 row_ror:8 row_mask:0xf bank_mask:0xf bound_ctrl:1
	v_add_f32_dpp v158, v158, v158 row_ror:4 row_mask:0xf bank_mask:0xf bound_ctrl:1
	v_add_f32_dpp v159, v159, v159 row_ror:4 row_mask:0xf bank_mask:0xf bound_ctrl:1
	v_add_f32_dpp v160, v160, v160 row_ror:4 row_mask:0xf bank_mask:0xf bound_ctrl:1
	v_add_f32_dpp v161, v161, v161 row_ror:4 row_mask:0xf bank_mask:0xf bound_ctrl:1
	v_add_f32_dpp v158, v158, v158 row_ror:2 row_mask:0xf bank_mask:0xf bound_ctrl:1
	v_add_f32_dpp v159, v159, v159 row_ror:2 row_mask:0xf bank_mask:0xf bound_ctrl:1
	v_add_f32_dpp v160, v160, v160 row_ror:2 row_mask:0xf bank_mask:0xf bound_ctrl:1
	v_add_f32_dpp v161, v161, v161 row_ror:2 row_mask:0xf bank_mask:0xf bound_ctrl:1
	v_add_f32_dpp v158, v158, v158 row_ror:1 row_mask:0xf bank_mask:0xf bound_ctrl:1
	v_add_f32_dpp v159, v159, v159 row_ror:1 row_mask:0xf bank_mask:0xf bound_ctrl:1
	v_add_f32_dpp v160, v160, v160 row_ror:1 row_mask:0xf bank_mask:0xf bound_ctrl:1
	v_add_f32_dpp v161, v161, v161 row_ror:1 row_mask:0xf bank_mask:0xf bound_ctrl:1
	v_mov_b32_e32 v254, v158
	v_mov_b32_dpp v254, v159 quad_perm:[0,1,2,3] row_mask:0xf bank_mask:0x2
	v_mov_b32_dpp v254, v160 quad_perm:[0,1,2,3] row_mask:0xf bank_mask:0x4
	v_mov_b32_dpp v254, v161 quad_perm:[0,1,2,3] row_mask:0xf bank_mask:0x8
	v_mul_f32_e32 v254, 0x49800000, v254
	v_trunc_f32_e32 v254, v254
	v_mul_f32_e32 v255, 0x2f800000, v254
	v_floor_f32_e32 v255, v255
	v_fmac_f32_e32 v254, 0xcf800000, v255
	v_cvt_u32_f32_e32 v36, v254
	v_cvt_u32_f32_e32 v37, v255
	s_waitcnt vmcnt(42)
; __device__ __forceinline__ float row16_sum(float v) { DPP_ADD(v, 0x128); DPP_ADD(v, 0x124); DPP_ADD(v, 0x122); DPP_ADD(v, 0x121); return v; }
; template <int EPI, int N, int K>
; __device__ __forceinline__ void gemm_phase(const bf16_t* __restrict__ A, const bf16_t* __restrict__ Bt, const EpiArgs ea) {
;     ...
;             const int row = brow + ai * 128 + wr * 64 + m * 16 + fq * 4 + j;
;             const u32x2 x2 = *(const u32x2*)(ea.outb + (size_t)row * DM + c0);
;             float4 xn;
;             xn.x = __builtin_bit_cast(float, x2[0] << 16) + acc[ai][0][m][0][j]; xn.y = __builtin_bit_cast(float, x2[0] & 0xffff0000u) + acc[ai][0][m][1][j];
;             xn.z = __builtin_bit_cast(float, x2[1] << 16) + acc[ai][1][m][0][j]; xn.w = __builtin_bit_cast(float, x2[1] & 0xffff0000u) + acc[ai][1][m][1][j];
;             u32x2 o = {pk2(xn.x, xn.y), pk2(xn.z, xn.w)};
;             st_wt(ea.outb + (size_t)row * DM + c0, o);
;             float ss = xn.x * xn.x + xn.y * xn.y + xn.z * xn.z + xn.w * xn.w;
;             ss = row16_sum(ss);
;             if (fr == 0) __hip_atomic_fetch_add(ea.rowsq_out + row, (rsq_t)(ss * RSQ_SCALE), __ATOMIC_RELAXED, __HIP_MEMORY_SCOPE_AGENT);
	v_lshlrev_b32_e32 v238, 16, v210
	v_and_b32_e32 v239, 0xffff0000, v210
	v_lshlrev_b32_e32 v240, 16, v211
	v_and_b32_e32 v241, 0xffff0000, v211
	v_lshlrev_b32_e32 v242, 16, v212
	v_and_b32_e32 v243, 0xffff0000, v212
	v_lshlrev_b32_e32 v244, 16, v213
	v_and_b32_e32 v245, 0xffff0000, v213
	v_lshlrev_b32_e32 v246, 16, v214
	v_and_b32_e32 v247, 0xffff0000, v214
	v_lshlrev_b32_e32 v248, 16, v215
	v_and_b32_e32 v249, 0xffff0000, v215
	v_lshlrev_b32_e32 v250, 16, v216
	v_and_b32_e32 v251, 0xffff0000, v216
	v_lshlrev_b32_e32 v252, 16, v217
	v_and_b32_e32 v253, 0xffff0000, v217
	v_add_f32_e32 v238, v20, v238
	v_add_f32_e32 v239, v16, v239
	v_add_f32_e32 v240, v28, v240
	v_add_f32_e32 v241, v24, v241
	v_add_f32_e32 v242, v21, v242
	v_add_f32_e32 v243, v17, v243
	v_add_f32_e32 v244, v29, v244
	v_add_f32_e32 v245, v25, v245
	v_add_f32_e32 v246, v22, v246
	v_add_f32_e32 v247, v18, v247
	v_add_f32_e32 v248, v30, v248
	v_add_f32_e32 v249, v26, v249
	v_add_f32_e32 v250, v23, v250
	v_add_f32_e32 v251, v19, v251
	v_add_f32_e32 v252, v31, v252
	v_add_f32_e32 v253, v27, v253
	v_cvt_pk_bf16_f32 v132, v238, v239
	v_cvt_pk_bf16_f32 v133, v240, v241
	v_cvt_pk_bf16_f32 v134, v242, v243
	v_cvt_pk_bf16_f32 v135, v244, v245
	v_cvt_pk_bf16_f32 v136, v246, v247
	v_cvt_pk_bf16_f32 v137, v248, v249
	v_cvt_pk_bf16_f32 v156, v250, v251
	v_cvt_pk_bf16_f32 v157, v252, v253
	v_add_u32_e32 v228, 0xa0000, v226
	global_store_dwordx2 v228, v[132:133], s[2:3] sc1
	v_add_u32_e32 v227, 0xa1000, v226
	global_store_dwordx2 v227, v[134:135], s[2:3] sc1
	v_add_u32_e32 v228, 0xa2000, v226
	global_store_dwordx2 v228, v[136:137], s[2:3] sc1
	v_add_u32_e32 v227, 0xa3000, v226
	global_store_dwordx2 v227, v[156:157], s[2:3] sc1
	v_pk_mul_f32 v[238:239], v[238:239], v[238:239]
	v_pk_mul_f32 v[240:241], v[240:241], v[240:241]
	v_pk_mul_f32 v[242:243], v[242:243], v[242:243]
	v_pk_mul_f32 v[244:245], v[244:245], v[244:245]
	v_pk_mul_f32 v[246:247], v[246:247], v[246:247]
	v_pk_mul_f32 v[248:249], v[248:249], v[248:249]
	v_pk_mul_f32 v[250:251], v[250:251], v[250:251]
	v_pk_mul_f32 v[252:253], v[252:253], v[252:253]
	v_add_f32_e32 v158, v238, v239
	v_add_f32_e32 v159, v242, v243
	v_add_f32_e32 v160, v246, v247
	v_add_f32_e32 v161, v250, v251
	v_add_f32_e32 v158, v240, v158
	v_add_f32_e32 v159, v244, v159
	v_add_f32_e32 v160, v248, v160
	v_add_f32_e32 v161, v252, v161
	v_add_f32_e32 v158, v241, v158
	v_add_f32_e32 v159, v245, v159
	v_add_f32_e32 v160, v249, v160
	v_add_f32_e32 v161, v253, v161
	v_add_f32_dpp v158, v158, v158 row_ror:8 row_mask:0xf bank_mask:0xf bound_ctrl:1
	v_add_f32_dpp v159, v159, v159 row_ror:8 row_mask:0xf bank_mask:0xf bound_ctrl:1
	v_add_f32_dpp v160, v160, v160 row_ror:8 row_mask:0xf bank_mask:0xf bound_ctrl:1
	v_add_f32_dpp v161, v161, v161 row_ror:8 row_mask:0xf bank_mask:0xf bound_ctrl:1
	v_add_f32_dpp v158, v158, v158 row_ror:4 row_mask:0xf bank_mask:0xf bound_ctrl:1
	v_add_f32_dpp v159, v159, v159 row_ror:4 row_mask:0xf bank_mask:0xf bound_ctrl:1
	v_add_f32_dpp v160, v160, v160 row_ror:4 row_mask:0xf bank_mask:0xf bound_ctrl:1
	v_add_f32_dpp v161, v161, v161 row_ror:4 row_mask:0xf bank_mask:0xf bound_ctrl:1
	v_add_f32_dpp v158, v158, v158 row_ror:2 row_mask:0xf bank_mask:0xf bound_ctrl:1
	v_add_f32_dpp v159, v159, v159 row_ror:2 row_mask:0xf bank_mask:0xf bound_ctrl:1
	v_add_f32_dpp v160, v160, v160 row_ror:2 row_mask:0xf bank_mask:0xf bound_ctrl:1
	v_add_f32_dpp v161, v161, v161 row_ror:2 row_mask:0xf bank_mask:0xf bound_ctrl:1
	v_add_f32_dpp v158, v158, v158 row_ror:1 row_mask:0xf bank_mask:0xf bound_ctrl:1
	v_add_f32_dpp v159, v159, v159 row_ror:1 row_mask:0xf bank_mask:0xf bound_ctrl:1
	v_add_f32_dpp v160, v160, v160 row_ror:1 row_mask:0xf bank_mask:0xf bound_ctrl:1
	v_add_f32_dpp v161, v161, v161 row_ror:1 row_mask:0xf bank_mask:0xf bound_ctrl:1
	v_mov_b32_e32 v254, v158
	v_mov_b32_dpp v254, v159 quad_perm:[0,1,2,3] row_mask:0xf bank_mask:0x2
	v_mov_b32_dpp v254, v160 quad_perm:[0,1,2,3] row_mask:0xf bank_mask:0x4
	v_mov_b32_dpp v254, v161 quad_perm:[0,1,2,3] row_mask:0xf bank_mask:0x8
	v_mul_f32_e32 v254, 0x49800000, v254
	v_trunc_f32_e32 v254, v254
	v_mul_f32_e32 v255, 0x2f800000, v254
	v_floor_f32_e32 v255, v255
	v_fmac_f32_e32 v254, 0xcf800000, v255
	v_cvt_u32_f32_e32 v20, v254
	v_cvt_u32_f32_e32 v21, v255
	s_waitcnt vmcnt(42)
; __device__ __forceinline__ float row16_sum(float v) { DPP_ADD(v, 0x128); DPP_ADD(v, 0x124); DPP_ADD(v, 0x122); DPP_ADD(v, 0x121); return v; }
; template <int EPI, int N, int K>
; __device__ __forceinline__ void gemm_phase(const bf16_t* __restrict__ A, const bf16_t* __restrict__ Bt, const EpiArgs ea) {
;     ...
;             const int row = brow + ai * 128 + wr * 64 + m * 16 + fq * 4 + j;
;             const u32x2 x2 = *(const u32x2*)(ea.outb + (size_t)row * DM + c0);
;             float4 xn;
;             xn.x = __builtin_bit_cast(float, x2[0] << 16) + acc[ai][0][m][0][j]; xn.y = __builtin_bit_cast(float, x2[0] & 0xffff0000u) + acc[ai][0][m][1][j];
;             xn.z = __builtin_bit_cast(float, x2[1] << 16) + acc[ai][1][m][0][j]; xn.w = __builtin_bit_cast(float, x2[1] & 0xffff0000u) + acc[ai][1][m][1][j];
;             u32x2 o = {pk2(xn.x, xn.y), pk2(xn.z, xn.w)};
;             st_wt(ea.outb + (size_t)row * DM + c0, o);
;             float ss = xn.x * xn.x + xn.y * xn.y + xn.z * xn.z + xn.w * xn.w;
;             ss = row16_sum(ss);
;             if (fr == 0) __hip_atomic_fetch_add(ea.rowsq_out + row, (rsq_t)(ss * RSQ_SCALE), __ATOMIC_RELAXED, __HIP_MEMORY_SCOPE_AGENT);
	v_lshlrev_b32_e32 v238, 16, v218
	v_and_b32_e32 v239, 0xffff0000, v218
	v_lshlrev_b32_e32 v240, 16, v219
	v_and_b32_e32 v241, 0xffff0000, v219
	v_lshlrev_b32_e32 v242, 16, v220
	v_and_b32_e32 v243, 0xffff0000, v220
	v_lshlrev_b32_e32 v244, 16, v221
	v_and_b32_e32 v245, 0xffff0000, v221
	v_lshlrev_b32_e32 v246, 16, v222
	v_and_b32_e32 v247, 0xffff0000, v222
	v_lshlrev_b32_e32 v248, 16, v223
	v_and_b32_e32 v249, 0xffff0000, v223
	v_lshlrev_b32_e32 v250, 16, v224
	v_and_b32_e32 v251, 0xffff0000, v224
	v_lshlrev_b32_e32 v252, 16, v225
	v_and_b32_e32 v253, 0xffff0000, v225
	v_add_f32_e32 v238, v8, v238
	v_add_f32_e32 v239, v12, v239
	v_add_f32_e32 v240, v4, v240
	v_add_f32_e32 v241, v0, v241
	v_add_f32_e32 v242, v9, v242
	v_add_f32_e32 v243, v13, v243
	v_add_f32_e32 v244, v5, v244
	v_add_f32_e32 v245, v1, v245
	v_add_f32_e32 v246, v10, v246
	v_add_f32_e32 v247, v14, v247
	v_add_f32_e32 v248, v6, v248
	v_add_f32_e32 v249, v2, v249
	v_add_f32_e32 v250, v11, v250
	v_add_f32_e32 v251, v15, v251
	v_add_f32_e32 v252, v7, v252
	v_add_f32_e32 v253, v3, v253
	v_cvt_pk_bf16_f32 v132, v238, v239
	v_cvt_pk_bf16_f32 v133, v240, v241
	v_cvt_pk_bf16_f32 v134, v242, v243
	v_cvt_pk_bf16_f32 v135, v244, v245
	v_cvt_pk_bf16_f32 v136, v246, v247
	v_cvt_pk_bf16_f32 v137, v248, v249
	v_cvt_pk_bf16_f32 v156, v250, v251
	v_cvt_pk_bf16_f32 v157, v252, v253
	v_add_u32_e32 v228, 0xb0000, v226
	global_store_dwordx2 v228, v[132:133], s[2:3] sc1
	v_add_u32_e32 v227, 0xb1000, v226
	global_store_dwordx2 v227, v[134:135], s[2:3] sc1
	v_add_u32_e32 v228, 0xb2000, v226
	global_store_dwordx2 v228, v[136:137], s[2:3] sc1
	v_add_u32_e32 v227, 0xb3000, v226
	global_store_dwordx2 v227, v[156:157], s[2:3] sc1
	v_pk_mul_f32 v[238:239], v[238:239], v[238:239]
	v_pk_mul_f32 v[240:241], v[240:241], v[240:241]
	v_pk_mul_f32 v[242:243], v[242:243], v[242:243]
	v_pk_mul_f32 v[244:245], v[244:245], v[244:245]
	v_pk_mul_f32 v[246:247], v[246:247], v[246:247]
	v_pk_mul_f32 v[248:249], v[248:249], v[248:249]
	v_pk_mul_f32 v[250:251], v[250:251], v[250:251]
	v_pk_mul_f32 v[252:253], v[252:253], v[252:253]
	v_add_f32_e32 v158, v238, v239
	v_add_f32_e32 v159, v242, v243
	v_add_f32_e32 v160, v246, v247
	v_add_f32_e32 v161, v250, v251
	v_add_f32_e32 v158, v240, v158
	v_add_f32_e32 v159, v244, v159
	v_add_f32_e32 v160, v248, v160
	v_add_f32_e32 v161, v252, v161
	v_add_f32_e32 v158, v241, v158
	v_add_f32_e32 v159, v245, v159
	v_add_f32_e32 v160, v249, v160
	v_add_f32_e32 v161, v253, v161
	v_add_f32_dpp v158, v158, v158 row_ror:8 row_mask:0xf bank_mask:0xf bound_ctrl:1
	v_add_f32_dpp v159, v159, v159 row_ror:8 row_mask:0xf bank_mask:0xf bound_ctrl:1
	v_add_f32_dpp v160, v160, v160 row_ror:8 row_mask:0xf bank_mask:0xf bound_ctrl:1
	v_add_f32_dpp v161, v161, v161 row_ror:8 row_mask:0xf bank_mask:0xf bound_ctrl:1
	v_add_f32_dpp v158, v158, v158 row_ror:4 row_mask:0xf bank_mask:0xf bound_ctrl:1
	v_add_f32_dpp v159, v159, v159 row_ror:4 row_mask:0xf bank_mask:0xf bound_ctrl:1
	v_add_f32_dpp v160, v160, v160 row_ror:4 row_mask:0xf bank_mask:0xf bound_ctrl:1
	v_add_f32_dpp v161, v161, v161 row_ror:4 row_mask:0xf bank_mask:0xf bound_ctrl:1
	v_add_f32_dpp v158, v158, v158 row_ror:2 row_mask:0xf bank_mask:0xf bound_ctrl:1
	v_add_f32_dpp v159, v159, v159 row_ror:2 row_mask:0xf bank_mask:0xf bound_ctrl:1
	v_add_f32_dpp v160, v160, v160 row_ror:2 row_mask:0xf bank_mask:0xf bound_ctrl:1
	v_add_f32_dpp v161, v161, v161 row_ror:2 row_mask:0xf bank_mask:0xf bound_ctrl:1
	v_add_f32_dpp v158, v158, v158 row_ror:1 row_mask:0xf bank_mask:0xf bound_ctrl:1
	v_add_f32_dpp v159, v159, v159 row_ror:1 row_mask:0xf bank_mask:0xf bound_ctrl:1
	v_add_f32_dpp v160, v160, v160 row_ror:1 row_mask:0xf bank_mask:0xf bound_ctrl:1
	v_add_f32_dpp v161, v161, v161 row_ror:1 row_mask:0xf bank_mask:0xf bound_ctrl:1
	v_mov_b32_e32 v254, v158
	v_mov_b32_dpp v254, v159 quad_perm:[0,1,2,3] row_mask:0xf bank_mask:0x2
	v_mov_b32_dpp v254, v160 quad_perm:[0,1,2,3] row_mask:0xf bank_mask:0x4
	v_mov_b32_dpp v254, v161 quad_perm:[0,1,2,3] row_mask:0xf bank_mask:0x8
	v_mul_f32_e32 v254, 0x49800000, v254
	v_trunc_f32_e32 v254, v254
	v_mul_f32_e32 v255, 0x2f800000, v254
	v_floor_f32_e32 v255, v255
	v_fmac_f32_e32 v254, 0xcf800000, v255
	v_cvt_u32_f32_e32 v8, v254
	v_cvt_u32_f32_e32 v9, v255
	v_and_b32_e32 v227, 12, v145
	v_cmp_eq_u32_e32 vcc, 0, v227
	s_and_b64 exec, exec, vcc
	ds_write_b64 v229, v[116:117]
	ds_write_b64 v229, v[100:101] offset:512
	ds_write_b64 v229, v[84:85] offset:1024
	ds_write_b64 v229, v[68:69] offset:1536
	ds_write_b64 v229, v[52:53] offset:2048
	ds_write_b64 v229, v[36:37] offset:2560
	ds_write_b64 v229, v[20:21] offset:3072
	ds_write_b64 v229, v[8:9] offset:3584
	s_mov_b64 exec, -1
	v_bfe_u32 v227, v146, 2, 2
	v_bfe_u32 v228, v145, 2, 4
	v_lshl_add_u32 v227, v227, 4, v228
	v_lshrrev_b32_e32 v228, 6, v145
	v_lshl_add_u32 v228, v228, 5, v227
	v_lshrrev_b32_e32 v230, 6, v146
	v_lshlrev_b32_e32 v231, 12, v230
	v_lshl_add_u32 v231, v228, 5, v231
	v_add_u32_e32 v231, 0x20410, v231
	v_cmp_gt_u32_e32 vcc, 32, v227
	v_lshrrev_b32_e32 v227, 6, v228
	v_lshlrev_b32_e32 v227, 7, v227
	v_and_b32_e32 v228, 63, v228
	v_add3_u32 v227, v227, v228, s29
	v_lshl_add_u32 v227, v230, 6, v227
	v_lshlrev_b32_e32 v227, 3, v227
	s_waitcnt lgkmcnt(0)
	s_barrier
	s_and_b64 exec, exec, vcc
	ds_read_b128 v[238:241], v231
	ds_read_b128 v[242:245], v231 offset:16
	s_waitcnt lgkmcnt(0)
	v_add_co_u32_e32 v246, vcc, v238, v240
	s_nop 1
	v_addc_co_u32_e32 v247, vcc, v239, v241, vcc
	v_add_co_u32_e32 v246, vcc, v246, v242
	s_nop 1
	v_addc_co_u32_e32 v247, vcc, v247, v243, vcc
	v_add_co_u32_e32 v246, vcc, v246, v244
	s_nop 1
	v_addc_co_u32_e32 v247, vcc, v247, v245, vcc
	global_atomic_add_x2 v227, v[246:247], s[0:1]
	s_mov_b64 exec, -1
	s_mov_b64 s[2:3], -1
	s_branch .LBB0_562
